# GEMM k-loops: first LDS-DMA piece issued right after the barrier, ahead of the fragment ds_reads
# speedup vs baseline: 1.0111x; 1.0042x over previous
.Lg0_top:
	s_waitcnt lgkmcnt(0)
	s_waitcnt vmcnt(0)
	s_barrier
	s_xor_b32 s87, s87, 0x10000
	s_mov_b32 m0, s87
	s_add_u32 s88, s60, s16
	s_addc_u32 s89, s61, s17
	global_load_lds_dwordx4 v144, s[88:89]
	ds_read_b128 v[156:159], v143
	ds_read_b128 v[160:163], v143 offset:2048
	ds_read_b128 v[164:167], v143 offset:4096
	ds_read_b128 v[168:171], v143 offset:6144
	ds_read_b128 v[190:193], v180 offset:32768
	ds_read_b128 v[194:197], v180 offset:34816
	ds_read_b128 v[198:201], v180 offset:36864
	ds_read_b128 v[202:205], v180 offset:38912
	v_mfma_f32_16x16x32_bf16 v[60:63], v[172:175], v[206:209], v[60:63]
	v_mfma_f32_16x16x32_bf16 v[52:55], v[172:175], v[210:213], v[52:55]
	s_add_u32 m0, s87, 0x2000
	s_add_u32 s88, s60, s18
	s_addc_u32 s89, s61, s19
	global_load_lds_dwordx4 v144, s[88:89]
	v_mfma_f32_16x16x32_bf16 v[56:59], v[172:175], v[214:217], v[56:59]
	v_mfma_f32_16x16x32_bf16 v[48:51], v[172:175], v[218:221], v[48:51]
	s_add_u32 m0, s87, 0x4000
	s_add_u32 s88, s60, s22
	s_addc_u32 s89, s61, s23
	global_load_lds_dwordx4 v144, s[88:89]
	v_mfma_f32_16x16x32_bf16 v[44:47], v[176:179], v[206:209], v[44:47]
	v_mfma_f32_16x16x32_bf16 v[36:39], v[176:179], v[210:213], v[36:39]
	s_add_u32 m0, s87, 0x6000
	s_add_u32 s88, s60, s40
	s_addc_u32 s89, s61, s41
	global_load_lds_dwordx4 v144, s[88:89]
	v_mfma_f32_16x16x32_bf16 v[40:43], v[176:179], v[214:217], v[40:43]
	v_mfma_f32_16x16x32_bf16 v[32:35], v[176:179], v[218:221], v[32:35]
	s_add_u32 m0, s87, 0x8000
	s_add_u32 s88, s60, s42
	s_addc_u32 s89, s61, s43
	global_load_lds_dwordx4 v145, s[88:89]
	v_mfma_f32_16x16x32_bf16 v[28:31], v[182:185], v[206:209], v[28:31]
	v_mfma_f32_16x16x32_bf16 v[16:19], v[182:185], v[210:213], v[16:19]
	s_add_u32 m0, s87, 0xa000
	s_add_u32 s88, s60, s52
	s_addc_u32 s89, s61, s53
	global_load_lds_dwordx4 v145, s[88:89]
	v_mfma_f32_16x16x32_bf16 v[24:27], v[182:185], v[214:217], v[24:27]
	v_mfma_f32_16x16x32_bf16 v[12:15], v[182:185], v[218:221], v[12:15]
	s_add_u32 m0, s87, 0xc000
	s_add_u32 s88, s60, s54
	s_addc_u32 s89, s61, s55
	global_load_lds_dwordx4 v145, s[88:89]
	v_mfma_f32_16x16x32_bf16 v[4:7], v[186:189], v[206:209], v[4:7]
	v_mfma_f32_16x16x32_bf16 v[0:3], v[186:189], v[210:213], v[0:3]
	s_add_u32 m0, s87, 0xe000
	s_add_u32 s88, s60, s56
	s_addc_u32 s89, s61, s57
	global_load_lds_dwordx4 v145, s[88:89]
	v_mfma_f32_16x16x32_bf16 v[20:23], v[186:189], v[214:217], v[20:23]
	v_mfma_f32_16x16x32_bf16 v[8:11], v[186:189], v[218:221], v[8:11]
.Lg0_entry:
	ds_read_b128 v[172:175], v143 offset:8192
	ds_read_b128 v[176:179], v143 offset:10240
	ds_read_b128 v[182:185], v143 offset:12288
	ds_read_b128 v[186:189], v143 offset:14336
	s_waitcnt lgkmcnt(4)
	v_mfma_f32_16x16x32_bf16 v[124:127], v[156:159], v[190:193], v[124:127]
	v_mfma_f32_16x16x32_bf16 v[116:119], v[156:159], v[194:197], v[116:119]
	v_mfma_f32_16x16x32_bf16 v[120:123], v[156:159], v[198:201], v[120:123]
	v_mfma_f32_16x16x32_bf16 v[112:115], v[156:159], v[202:205], v[112:115]
	v_mfma_f32_16x16x32_bf16 v[108:111], v[160:163], v[190:193], v[108:111]
	v_mfma_f32_16x16x32_bf16 v[100:103], v[160:163], v[194:197], v[100:103]
	v_mfma_f32_16x16x32_bf16 v[104:107], v[160:163], v[198:201], v[104:107]
	v_mfma_f32_16x16x32_bf16 v[96:99], v[160:163], v[202:205], v[96:99]
	v_mfma_f32_16x16x32_bf16 v[92:95], v[164:167], v[190:193], v[92:95]
	v_mfma_f32_16x16x32_bf16 v[84:87], v[164:167], v[194:197], v[84:87]
	v_mfma_f32_16x16x32_bf16 v[88:91], v[164:167], v[198:201], v[88:91]
	v_mfma_f32_16x16x32_bf16 v[80:83], v[164:167], v[202:205], v[80:83]
	v_mfma_f32_16x16x32_bf16 v[76:79], v[168:171], v[190:193], v[76:79]
	v_mfma_f32_16x16x32_bf16 v[68:71], v[168:171], v[194:197], v[68:71]
	v_mfma_f32_16x16x32_bf16 v[72:75], v[168:171], v[198:201], v[72:75]
	v_mfma_f32_16x16x32_bf16 v[64:67], v[168:171], v[202:205], v[64:67]
	ds_read_b128 v[156:159], v155
	ds_read_b128 v[160:163], v155 offset:2048
	ds_read_b128 v[164:167], v155 offset:4096
	ds_read_b128 v[168:171], v155 offset:6144
	ds_read_b128 v[206:209], v222 offset:32768
	ds_read_b128 v[210:213], v222 offset:34816
	ds_read_b128 v[214:217], v222 offset:36864
	ds_read_b128 v[218:221], v222 offset:38912
	s_waitcnt lgkmcnt(8)
	v_mfma_f32_16x16x32_bf16 v[60:63], v[172:175], v[190:193], v[60:63]
	v_mfma_f32_16x16x32_bf16 v[52:55], v[172:175], v[194:197], v[52:55]
	v_mfma_f32_16x16x32_bf16 v[56:59], v[172:175], v[198:201], v[56:59]
	v_mfma_f32_16x16x32_bf16 v[48:51], v[172:175], v[202:205], v[48:51]
	v_mfma_f32_16x16x32_bf16 v[44:47], v[176:179], v[190:193], v[44:47]
	v_mfma_f32_16x16x32_bf16 v[36:39], v[176:179], v[194:197], v[36:39]
	v_mfma_f32_16x16x32_bf16 v[40:43], v[176:179], v[198:201], v[40:43]
	v_mfma_f32_16x16x32_bf16 v[32:35], v[176:179], v[202:205], v[32:35]
	v_mfma_f32_16x16x32_bf16 v[28:31], v[182:185], v[190:193], v[28:31]
	v_mfma_f32_16x16x32_bf16 v[16:19], v[182:185], v[194:197], v[16:19]
	v_mfma_f32_16x16x32_bf16 v[24:27], v[182:185], v[198:201], v[24:27]
	v_mfma_f32_16x16x32_bf16 v[12:15], v[182:185], v[202:205], v[12:15]
	v_mfma_f32_16x16x32_bf16 v[4:7], v[186:189], v[190:193], v[4:7]
	v_mfma_f32_16x16x32_bf16 v[0:3], v[186:189], v[194:197], v[0:3]
	v_mfma_f32_16x16x32_bf16 v[20:23], v[186:189], v[198:201], v[20:23]
	v_mfma_f32_16x16x32_bf16 v[8:11], v[186:189], v[202:205], v[8:11]
	ds_read_b128 v[172:175], v155 offset:8192
	ds_read_b128 v[176:179], v155 offset:10240
	ds_read_b128 v[182:185], v155 offset:12288
	ds_read_b128 v[186:189], v155 offset:14336
	s_waitcnt lgkmcnt(4)
	v_mfma_f32_16x16x32_bf16 v[124:127], v[156:159], v[206:209], v[124:127]
	v_mfma_f32_16x16x32_bf16 v[116:119], v[156:159], v[210:213], v[116:119]
	v_mfma_f32_16x16x32_bf16 v[120:123], v[156:159], v[214:217], v[120:123]
	v_mfma_f32_16x16x32_bf16 v[112:115], v[156:159], v[218:221], v[112:115]
	v_mfma_f32_16x16x32_bf16 v[108:111], v[160:163], v[206:209], v[108:111]
	v_mfma_f32_16x16x32_bf16 v[100:103], v[160:163], v[210:213], v[100:103]
	v_mfma_f32_16x16x32_bf16 v[104:107], v[160:163], v[214:217], v[104:107]
	v_mfma_f32_16x16x32_bf16 v[96:99], v[160:163], v[218:221], v[96:99]
	v_mfma_f32_16x16x32_bf16 v[92:95], v[164:167], v[206:209], v[92:95]
	v_mfma_f32_16x16x32_bf16 v[84:87], v[164:167], v[210:213], v[84:87]
	v_mfma_f32_16x16x32_bf16 v[88:91], v[164:167], v[214:217], v[88:91]
	v_mfma_f32_16x16x32_bf16 v[80:83], v[164:167], v[218:221], v[80:83]
	v_mfma_f32_16x16x32_bf16 v[76:79], v[168:171], v[206:209], v[76:79]
	v_mfma_f32_16x16x32_bf16 v[68:71], v[168:171], v[210:213], v[68:71]
	v_mfma_f32_16x16x32_bf16 v[72:75], v[168:171], v[214:217], v[72:75]
	v_mfma_f32_16x16x32_bf16 v[64:67], v[168:171], v[218:221], v[64:67]
	s_add_u32 s60, s60, 0x80
	s_addc_u32 s61, s61, 0
	s_add_i32 s59, s59, 1
	s_cmp_lt_u32 s59, 15
	s_cbranch_scc0 .Lg0_last
	s_waitcnt lgkmcnt(0)
	s_waitcnt vmcnt(0)
	s_barrier
	s_xor_b32 s87, s87, 0x10000
	s_mov_b32 m0, s87
	s_add_u32 s88, s60, s16
	s_addc_u32 s89, s61, s17
	global_load_lds_dwordx4 v144, s[88:89]
	ds_read_b128 v[156:159], v223
	ds_read_b128 v[160:163], v223 offset:2048
	ds_read_b128 v[164:167], v223 offset:4096
	ds_read_b128 v[168:171], v223 offset:6144
	ds_read_b128 v[190:193], v225 offset:32768
	ds_read_b128 v[194:197], v225 offset:34816
	ds_read_b128 v[198:201], v225 offset:36864
	ds_read_b128 v[202:205], v225 offset:38912
	v_mfma_f32_16x16x32_bf16 v[60:63], v[172:175], v[206:209], v[60:63]
	v_mfma_f32_16x16x32_bf16 v[52:55], v[172:175], v[210:213], v[52:55]
	s_add_u32 m0, s87, 0x2000
	s_add_u32 s88, s60, s18
	s_addc_u32 s89, s61, s19
	global_load_lds_dwordx4 v144, s[88:89]
	v_mfma_f32_16x16x32_bf16 v[56:59], v[172:175], v[214:217], v[56:59]
	v_mfma_f32_16x16x32_bf16 v[48:51], v[172:175], v[218:221], v[48:51]
	s_add_u32 m0, s87, 0x4000
	s_add_u32 s88, s60, s22
	s_addc_u32 s89, s61, s23
	global_load_lds_dwordx4 v144, s[88:89]
	v_mfma_f32_16x16x32_bf16 v[44:47], v[176:179], v[206:209], v[44:47]
	v_mfma_f32_16x16x32_bf16 v[36:39], v[176:179], v[210:213], v[36:39]
	s_add_u32 m0, s87, 0x6000
	s_add_u32 s88, s60, s40
	s_addc_u32 s89, s61, s41
	global_load_lds_dwordx4 v144, s[88:89]
	v_mfma_f32_16x16x32_bf16 v[40:43], v[176:179], v[214:217], v[40:43]
	v_mfma_f32_16x16x32_bf16 v[32:35], v[176:179], v[218:221], v[32:35]
	s_add_u32 m0, s87, 0x8000
	s_add_u32 s88, s60, s42
	s_addc_u32 s89, s61, s43
	global_load_lds_dwordx4 v145, s[88:89]
	v_mfma_f32_16x16x32_bf16 v[28:31], v[182:185], v[206:209], v[28:31]
	v_mfma_f32_16x16x32_bf16 v[16:19], v[182:185], v[210:213], v[16:19]
	s_add_u32 m0, s87, 0xa000
	s_add_u32 s88, s60, s52
	s_addc_u32 s89, s61, s53
	global_load_lds_dwordx4 v145, s[88:89]
	v_mfma_f32_16x16x32_bf16 v[24:27], v[182:185], v[214:217], v[24:27]
	v_mfma_f32_16x16x32_bf16 v[12:15], v[182:185], v[218:221], v[12:15]
	s_add_u32 m0, s87, 0xc000
	s_add_u32 s88, s60, s54
	s_addc_u32 s89, s61, s55
	global_load_lds_dwordx4 v145, s[88:89]
	v_mfma_f32_16x16x32_bf16 v[4:7], v[186:189], v[206:209], v[4:7]
	v_mfma_f32_16x16x32_bf16 v[0:3], v[186:189], v[210:213], v[0:3]
	s_add_u32 m0, s87, 0xe000
	s_add_u32 s88, s60, s56
	s_addc_u32 s89, s61, s57
	global_load_lds_dwordx4 v145, s[88:89]
	v_mfma_f32_16x16x32_bf16 v[20:23], v[186:189], v[214:217], v[20:23]
	v_mfma_f32_16x16x32_bf16 v[8:11], v[186:189], v[218:221], v[8:11]
	ds_read_b128 v[172:175], v223 offset:8192
	ds_read_b128 v[176:179], v223 offset:10240
	ds_read_b128 v[182:185], v223 offset:12288
	ds_read_b128 v[186:189], v223 offset:14336
	s_waitcnt lgkmcnt(4)
	v_mfma_f32_16x16x32_bf16 v[124:127], v[156:159], v[190:193], v[124:127]
	v_mfma_f32_16x16x32_bf16 v[116:119], v[156:159], v[194:197], v[116:119]
	v_mfma_f32_16x16x32_bf16 v[120:123], v[156:159], v[198:201], v[120:123]
	v_mfma_f32_16x16x32_bf16 v[112:115], v[156:159], v[202:205], v[112:115]
	v_mfma_f32_16x16x32_bf16 v[108:111], v[160:163], v[190:193], v[108:111]
	v_mfma_f32_16x16x32_bf16 v[100:103], v[160:163], v[194:197], v[100:103]
	v_mfma_f32_16x16x32_bf16 v[104:107], v[160:163], v[198:201], v[104:107]
	v_mfma_f32_16x16x32_bf16 v[96:99], v[160:163], v[202:205], v[96:99]
	v_mfma_f32_16x16x32_bf16 v[92:95], v[164:167], v[190:193], v[92:95]
	v_mfma_f32_16x16x32_bf16 v[84:87], v[164:167], v[194:197], v[84:87]
	v_mfma_f32_16x16x32_bf16 v[88:91], v[164:167], v[198:201], v[88:91]
	v_mfma_f32_16x16x32_bf16 v[80:83], v[164:167], v[202:205], v[80:83]
	v_mfma_f32_16x16x32_bf16 v[76:79], v[168:171], v[190:193], v[76:79]
	v_mfma_f32_16x16x32_bf16 v[68:71], v[168:171], v[194:197], v[68:71]
	v_mfma_f32_16x16x32_bf16 v[72:75], v[168:171], v[198:201], v[72:75]
	v_mfma_f32_16x16x32_bf16 v[64:67], v[168:171], v[202:205], v[64:67]
	ds_read_b128 v[156:159], v224
	ds_read_b128 v[160:163], v224 offset:2048
	ds_read_b128 v[164:167], v224 offset:4096
	ds_read_b128 v[168:171], v224 offset:6144
	ds_read_b128 v[206:209], v226 offset:32768
	ds_read_b128 v[210:213], v226 offset:34816
	ds_read_b128 v[214:217], v226 offset:36864
	ds_read_b128 v[218:221], v226 offset:38912
	s_waitcnt lgkmcnt(8)
	v_mfma_f32_16x16x32_bf16 v[60:63], v[172:175], v[190:193], v[60:63]
	v_mfma_f32_16x16x32_bf16 v[52:55], v[172:175], v[194:197], v[52:55]
	v_mfma_f32_16x16x32_bf16 v[56:59], v[172:175], v[198:201], v[56:59]
	v_mfma_f32_16x16x32_bf16 v[48:51], v[172:175], v[202:205], v[48:51]
	v_mfma_f32_16x16x32_bf16 v[44:47], v[176:179], v[190:193], v[44:47]
	v_mfma_f32_16x16x32_bf16 v[36:39], v[176:179], v[194:197], v[36:39]
	v_mfma_f32_16x16x32_bf16 v[40:43], v[176:179], v[198:201], v[40:43]
	v_mfma_f32_16x16x32_bf16 v[32:35], v[176:179], v[202:205], v[32:35]
	v_mfma_f32_16x16x32_bf16 v[28:31], v[182:185], v[190:193], v[28:31]
	v_mfma_f32_16x16x32_bf16 v[16:19], v[182:185], v[194:197], v[16:19]
	v_mfma_f32_16x16x32_bf16 v[24:27], v[182:185], v[198:201], v[24:27]
	v_mfma_f32_16x16x32_bf16 v[12:15], v[182:185], v[202:205], v[12:15]
	v_mfma_f32_16x16x32_bf16 v[4:7], v[186:189], v[190:193], v[4:7]
	v_mfma_f32_16x16x32_bf16 v[0:3], v[186:189], v[194:197], v[0:3]
	v_mfma_f32_16x16x32_bf16 v[20:23], v[186:189], v[198:201], v[20:23]
	v_mfma_f32_16x16x32_bf16 v[8:11], v[186:189], v[202:205], v[8:11]
	ds_read_b128 v[172:175], v224 offset:8192
	ds_read_b128 v[176:179], v224 offset:10240
	ds_read_b128 v[182:185], v224 offset:12288
	ds_read_b128 v[186:189], v224 offset:14336
	s_waitcnt lgkmcnt(4)
	v_mfma_f32_16x16x32_bf16 v[124:127], v[156:159], v[206:209], v[124:127]
	v_mfma_f32_16x16x32_bf16 v[116:119], v[156:159], v[210:213], v[116:119]
	v_mfma_f32_16x16x32_bf16 v[120:123], v[156:159], v[214:217], v[120:123]
	v_mfma_f32_16x16x32_bf16 v[112:115], v[156:159], v[218:221], v[112:115]
	v_mfma_f32_16x16x32_bf16 v[108:111], v[160:163], v[206:209], v[108:111]
	v_mfma_f32_16x16x32_bf16 v[100:103], v[160:163], v[210:213], v[100:103]
	v_mfma_f32_16x16x32_bf16 v[104:107], v[160:163], v[214:217], v[104:107]
	v_mfma_f32_16x16x32_bf16 v[96:99], v[160:163], v[218:221], v[96:99]
	v_mfma_f32_16x16x32_bf16 v[92:95], v[164:167], v[206:209], v[92:95]
	v_mfma_f32_16x16x32_bf16 v[84:87], v[164:167], v[210:213], v[84:87]
	v_mfma_f32_16x16x32_bf16 v[88:91], v[164:167], v[214:217], v[88:91]
	v_mfma_f32_16x16x32_bf16 v[80:83], v[164:167], v[218:221], v[80:83]
	v_mfma_f32_16x16x32_bf16 v[76:79], v[168:171], v[206:209], v[76:79]
	v_mfma_f32_16x16x32_bf16 v[68:71], v[168:171], v[210:213], v[68:71]
	v_mfma_f32_16x16x32_bf16 v[72:75], v[168:171], v[214:217], v[72:75]
	v_mfma_f32_16x16x32_bf16 v[64:67], v[168:171], v[218:221], v[64:67]
	s_add_u32 s60, s60, 0x80
	s_addc_u32 s61, s61, 0
	s_add_i32 s59, s59, 1
	s_branch .Lg0_top

.Lg1_top:
	s_waitcnt lgkmcnt(0)
	s_waitcnt vmcnt(0)
	s_barrier
	s_xor_b32 s59, s59, 0x10000
	s_mov_b32 m0, s59
	s_add_u32 s52, s50, s14
	s_addc_u32 s53, s51, s15
	global_load_lds_dwordx4 v178, s[52:53]
	ds_read_b128 v[142:145], v141
	ds_read_b128 v[146:149], v141 offset:2048
	ds_read_b128 v[150:153], v141 offset:4096
	ds_read_b128 v[154:157], v141 offset:6144
	ds_read_b128 v[174:177], v210 offset:32768
	ds_read_b128 v[182:185], v210 offset:34816
	ds_read_b128 v[186:189], v210 offset:36864
	ds_read_b128 v[190:193], v210 offset:38912
	v_mfma_f32_16x16x32_bf16 v[60:63], v[158:161], v[194:197], v[60:63]
	v_mfma_f32_16x16x32_bf16 v[56:59], v[158:161], v[198:201], v[56:59]
	s_add_u32 m0, s59, 0x2000
	s_add_u32 s52, s50, s16
	s_addc_u32 s53, s51, s17
	global_load_lds_dwordx4 v178, s[52:53]
	v_mfma_f32_16x16x32_bf16 v[52:55], v[158:161], v[202:205], v[52:55]
	v_mfma_f32_16x16x32_bf16 v[48:51], v[158:161], v[206:209], v[48:51]
	s_add_u32 m0, s59, 0x4000
	s_add_u32 s52, s50, s18
	s_addc_u32 s53, s51, s19
	global_load_lds_dwordx4 v178, s[52:53]
	v_mfma_f32_16x16x32_bf16 v[44:47], v[162:165], v[194:197], v[44:47]
	v_mfma_f32_16x16x32_bf16 v[40:43], v[162:165], v[198:201], v[40:43]
	s_add_u32 m0, s59, 0x6000
	s_add_u32 s52, s50, s22
	s_addc_u32 s53, s51, s23
	global_load_lds_dwordx4 v178, s[52:53]
	v_mfma_f32_16x16x32_bf16 v[36:39], v[162:165], v[202:205], v[36:39]
	v_mfma_f32_16x16x32_bf16 v[32:35], v[162:165], v[206:209], v[32:35]
	s_add_u32 m0, s59, 0x8000
	s_add_u32 s52, s50, s40
	s_addc_u32 s53, s51, s41
	global_load_lds_dwordx4 v179, s[52:53]
	v_mfma_f32_16x16x32_bf16 v[28:31], v[166:169], v[194:197], v[28:31]
	v_mfma_f32_16x16x32_bf16 v[20:23], v[166:169], v[198:201], v[20:23]
	s_add_u32 m0, s59, 0xa000
	s_add_u32 s52, s50, s42
	s_addc_u32 s53, s51, s43
	global_load_lds_dwordx4 v179, s[52:53]
	v_mfma_f32_16x16x32_bf16 v[16:19], v[166:169], v[202:205], v[16:19]
	v_mfma_f32_16x16x32_bf16 v[8:11], v[166:169], v[206:209], v[8:11]
	s_add_u32 m0, s59, 0xc000
	s_add_u32 s52, s50, s44
	s_addc_u32 s53, s51, s45
	global_load_lds_dwordx4 v179, s[52:53]
	v_mfma_f32_16x16x32_bf16 v[4:7], v[170:173], v[194:197], v[4:7]
	v_mfma_f32_16x16x32_bf16 v[0:3], v[170:173], v[198:201], v[0:3]
	s_add_u32 m0, s59, 0xe000
	s_add_u32 s52, s50, s46
	s_addc_u32 s53, s51, s47
	global_load_lds_dwordx4 v179, s[52:53]
	v_mfma_f32_16x16x32_bf16 v[24:27], v[170:173], v[202:205], v[24:27]
	v_mfma_f32_16x16x32_bf16 v[12:15], v[170:173], v[206:209], v[12:15]
.Lg1_entry:
	ds_read_b128 v[158:161], v141 offset:8192
	ds_read_b128 v[162:165], v141 offset:10240
	ds_read_b128 v[166:169], v141 offset:12288
	ds_read_b128 v[170:173], v141 offset:14336
	s_waitcnt lgkmcnt(4)
	v_mfma_f32_16x16x32_bf16 v[124:127], v[142:145], v[174:177], v[124:127]
	v_mfma_f32_16x16x32_bf16 v[120:123], v[142:145], v[182:185], v[120:123]
	v_mfma_f32_16x16x32_bf16 v[116:119], v[142:145], v[186:189], v[116:119]
	v_mfma_f32_16x16x32_bf16 v[112:115], v[142:145], v[190:193], v[112:115]
	v_mfma_f32_16x16x32_bf16 v[108:111], v[146:149], v[174:177], v[108:111]
	v_mfma_f32_16x16x32_bf16 v[104:107], v[146:149], v[182:185], v[104:107]
	v_mfma_f32_16x16x32_bf16 v[100:103], v[146:149], v[186:189], v[100:103]
	v_mfma_f32_16x16x32_bf16 v[96:99], v[146:149], v[190:193], v[96:99]
	v_mfma_f32_16x16x32_bf16 v[92:95], v[150:153], v[174:177], v[92:95]
	v_mfma_f32_16x16x32_bf16 v[88:91], v[150:153], v[182:185], v[88:91]
	v_mfma_f32_16x16x32_bf16 v[84:87], v[150:153], v[186:189], v[84:87]
	v_mfma_f32_16x16x32_bf16 v[80:83], v[150:153], v[190:193], v[80:83]
	v_mfma_f32_16x16x32_bf16 v[76:79], v[154:157], v[174:177], v[76:79]
	v_mfma_f32_16x16x32_bf16 v[72:75], v[154:157], v[182:185], v[72:75]
	v_mfma_f32_16x16x32_bf16 v[68:71], v[154:157], v[186:189], v[68:71]
	v_mfma_f32_16x16x32_bf16 v[64:67], v[154:157], v[190:193], v[64:67]
	ds_read_b128 v[142:145], v180
	ds_read_b128 v[146:149], v180 offset:2048
	ds_read_b128 v[150:153], v180 offset:4096
	ds_read_b128 v[154:157], v180 offset:6144
	ds_read_b128 v[194:197], v211 offset:32768
	ds_read_b128 v[198:201], v211 offset:34816
	ds_read_b128 v[202:205], v211 offset:36864
	ds_read_b128 v[206:209], v211 offset:38912
	s_waitcnt lgkmcnt(8)
	v_mfma_f32_16x16x32_bf16 v[60:63], v[158:161], v[174:177], v[60:63]
	v_mfma_f32_16x16x32_bf16 v[56:59], v[158:161], v[182:185], v[56:59]
	v_mfma_f32_16x16x32_bf16 v[52:55], v[158:161], v[186:189], v[52:55]
	v_mfma_f32_16x16x32_bf16 v[48:51], v[158:161], v[190:193], v[48:51]
	v_mfma_f32_16x16x32_bf16 v[44:47], v[162:165], v[174:177], v[44:47]
	v_mfma_f32_16x16x32_bf16 v[40:43], v[162:165], v[182:185], v[40:43]
	v_mfma_f32_16x16x32_bf16 v[36:39], v[162:165], v[186:189], v[36:39]
	v_mfma_f32_16x16x32_bf16 v[32:35], v[162:165], v[190:193], v[32:35]
	v_mfma_f32_16x16x32_bf16 v[28:31], v[166:169], v[174:177], v[28:31]
	v_mfma_f32_16x16x32_bf16 v[20:23], v[166:169], v[182:185], v[20:23]
	v_mfma_f32_16x16x32_bf16 v[16:19], v[166:169], v[186:189], v[16:19]
	v_mfma_f32_16x16x32_bf16 v[8:11], v[166:169], v[190:193], v[8:11]
	v_mfma_f32_16x16x32_bf16 v[4:7], v[170:173], v[174:177], v[4:7]
	v_mfma_f32_16x16x32_bf16 v[0:3], v[170:173], v[182:185], v[0:3]
	v_mfma_f32_16x16x32_bf16 v[24:27], v[170:173], v[186:189], v[24:27]
	v_mfma_f32_16x16x32_bf16 v[12:15], v[170:173], v[190:193], v[12:15]
	ds_read_b128 v[158:161], v180 offset:8192
	ds_read_b128 v[162:165], v180 offset:10240
	ds_read_b128 v[166:169], v180 offset:12288
	ds_read_b128 v[170:173], v180 offset:14336
	s_waitcnt lgkmcnt(4)
	v_mfma_f32_16x16x32_bf16 v[124:127], v[142:145], v[194:197], v[124:127]
	v_mfma_f32_16x16x32_bf16 v[120:123], v[142:145], v[198:201], v[120:123]
	v_mfma_f32_16x16x32_bf16 v[116:119], v[142:145], v[202:205], v[116:119]
	v_mfma_f32_16x16x32_bf16 v[112:115], v[142:145], v[206:209], v[112:115]
	v_mfma_f32_16x16x32_bf16 v[108:111], v[146:149], v[194:197], v[108:111]
	v_mfma_f32_16x16x32_bf16 v[104:107], v[146:149], v[198:201], v[104:107]
	v_mfma_f32_16x16x32_bf16 v[100:103], v[146:149], v[202:205], v[100:103]
	v_mfma_f32_16x16x32_bf16 v[96:99], v[146:149], v[206:209], v[96:99]
	v_mfma_f32_16x16x32_bf16 v[92:95], v[150:153], v[194:197], v[92:95]
	v_mfma_f32_16x16x32_bf16 v[88:91], v[150:153], v[198:201], v[88:91]
	v_mfma_f32_16x16x32_bf16 v[84:87], v[150:153], v[202:205], v[84:87]
	v_mfma_f32_16x16x32_bf16 v[80:83], v[150:153], v[206:209], v[80:83]
	v_mfma_f32_16x16x32_bf16 v[76:79], v[154:157], v[194:197], v[76:79]
	v_mfma_f32_16x16x32_bf16 v[72:75], v[154:157], v[198:201], v[72:75]
	v_mfma_f32_16x16x32_bf16 v[68:71], v[154:157], v[202:205], v[68:71]
	v_mfma_f32_16x16x32_bf16 v[64:67], v[154:157], v[206:209], v[64:67]
	s_add_u32 s50, s50, 0x80
	s_addc_u32 s51, s51, 0
	s_add_i32 s49, s49, 1
	s_cmp_lt_u32 s49, 31
	s_cbranch_scc0 .Lg1_last
	s_waitcnt lgkmcnt(0)
	s_waitcnt vmcnt(0)
	s_barrier
	s_xor_b32 s59, s59, 0x10000
	s_mov_b32 m0, s59
	s_add_u32 s52, s50, s14
	s_addc_u32 s53, s51, s15
	global_load_lds_dwordx4 v178, s[52:53]
	ds_read_b128 v[142:145], v212
	ds_read_b128 v[146:149], v212 offset:2048
	ds_read_b128 v[150:153], v212 offset:4096
	ds_read_b128 v[154:157], v212 offset:6144
	ds_read_b128 v[174:177], v214 offset:32768
	ds_read_b128 v[182:185], v214 offset:34816
	ds_read_b128 v[186:189], v214 offset:36864
	ds_read_b128 v[190:193], v214 offset:38912
	v_mfma_f32_16x16x32_bf16 v[60:63], v[158:161], v[194:197], v[60:63]
	v_mfma_f32_16x16x32_bf16 v[56:59], v[158:161], v[198:201], v[56:59]
	s_add_u32 m0, s59, 0x2000
	s_add_u32 s52, s50, s16
	s_addc_u32 s53, s51, s17
	global_load_lds_dwordx4 v178, s[52:53]
	v_mfma_f32_16x16x32_bf16 v[52:55], v[158:161], v[202:205], v[52:55]
	v_mfma_f32_16x16x32_bf16 v[48:51], v[158:161], v[206:209], v[48:51]
	s_add_u32 m0, s59, 0x4000
	s_add_u32 s52, s50, s18
	s_addc_u32 s53, s51, s19
	global_load_lds_dwordx4 v178, s[52:53]
	v_mfma_f32_16x16x32_bf16 v[44:47], v[162:165], v[194:197], v[44:47]
	v_mfma_f32_16x16x32_bf16 v[40:43], v[162:165], v[198:201], v[40:43]
	s_add_u32 m0, s59, 0x6000
	s_add_u32 s52, s50, s22
	s_addc_u32 s53, s51, s23
	global_load_lds_dwordx4 v178, s[52:53]
	v_mfma_f32_16x16x32_bf16 v[36:39], v[162:165], v[202:205], v[36:39]
	v_mfma_f32_16x16x32_bf16 v[32:35], v[162:165], v[206:209], v[32:35]
	s_add_u32 m0, s59, 0x8000
	s_add_u32 s52, s50, s40
	s_addc_u32 s53, s51, s41
	global_load_lds_dwordx4 v179, s[52:53]
	v_mfma_f32_16x16x32_bf16 v[28:31], v[166:169], v[194:197], v[28:31]
	v_mfma_f32_16x16x32_bf16 v[20:23], v[166:169], v[198:201], v[20:23]
	s_add_u32 m0, s59, 0xa000
	s_add_u32 s52, s50, s42
	s_addc_u32 s53, s51, s43
	global_load_lds_dwordx4 v179, s[52:53]
	v_mfma_f32_16x16x32_bf16 v[16:19], v[166:169], v[202:205], v[16:19]
	v_mfma_f32_16x16x32_bf16 v[8:11], v[166:169], v[206:209], v[8:11]
	s_add_u32 m0, s59, 0xc000
	s_add_u32 s52, s50, s44
	s_addc_u32 s53, s51, s45
	global_load_lds_dwordx4 v179, s[52:53]
	v_mfma_f32_16x16x32_bf16 v[4:7], v[170:173], v[194:197], v[4:7]
	v_mfma_f32_16x16x32_bf16 v[0:3], v[170:173], v[198:201], v[0:3]
	s_add_u32 m0, s59, 0xe000
	s_add_u32 s52, s50, s46
	s_addc_u32 s53, s51, s47
	global_load_lds_dwordx4 v179, s[52:53]
	v_mfma_f32_16x16x32_bf16 v[24:27], v[170:173], v[202:205], v[24:27]
	v_mfma_f32_16x16x32_bf16 v[12:15], v[170:173], v[206:209], v[12:15]
	ds_read_b128 v[158:161], v212 offset:8192
	ds_read_b128 v[162:165], v212 offset:10240
	ds_read_b128 v[166:169], v212 offset:12288
	ds_read_b128 v[170:173], v212 offset:14336
	s_waitcnt lgkmcnt(4)
	v_mfma_f32_16x16x32_bf16 v[124:127], v[142:145], v[174:177], v[124:127]
	v_mfma_f32_16x16x32_bf16 v[120:123], v[142:145], v[182:185], v[120:123]
	v_mfma_f32_16x16x32_bf16 v[116:119], v[142:145], v[186:189], v[116:119]
	v_mfma_f32_16x16x32_bf16 v[112:115], v[142:145], v[190:193], v[112:115]
	v_mfma_f32_16x16x32_bf16 v[108:111], v[146:149], v[174:177], v[108:111]
	v_mfma_f32_16x16x32_bf16 v[104:107], v[146:149], v[182:185], v[104:107]
	v_mfma_f32_16x16x32_bf16 v[100:103], v[146:149], v[186:189], v[100:103]
	v_mfma_f32_16x16x32_bf16 v[96:99], v[146:149], v[190:193], v[96:99]
	v_mfma_f32_16x16x32_bf16 v[92:95], v[150:153], v[174:177], v[92:95]
	v_mfma_f32_16x16x32_bf16 v[88:91], v[150:153], v[182:185], v[88:91]
	v_mfma_f32_16x16x32_bf16 v[84:87], v[150:153], v[186:189], v[84:87]
	v_mfma_f32_16x16x32_bf16 v[80:83], v[150:153], v[190:193], v[80:83]
	v_mfma_f32_16x16x32_bf16 v[76:79], v[154:157], v[174:177], v[76:79]
	v_mfma_f32_16x16x32_bf16 v[72:75], v[154:157], v[182:185], v[72:75]
	v_mfma_f32_16x16x32_bf16 v[68:71], v[154:157], v[186:189], v[68:71]
	v_mfma_f32_16x16x32_bf16 v[64:67], v[154:157], v[190:193], v[64:67]
	ds_read_b128 v[142:145], v213
	ds_read_b128 v[146:149], v213 offset:2048
	ds_read_b128 v[150:153], v213 offset:4096
	ds_read_b128 v[154:157], v213 offset:6144
	ds_read_b128 v[194:197], v215 offset:32768
	ds_read_b128 v[198:201], v215 offset:34816
	ds_read_b128 v[202:205], v215 offset:36864
	ds_read_b128 v[206:209], v215 offset:38912
	s_waitcnt lgkmcnt(8)
	v_mfma_f32_16x16x32_bf16 v[60:63], v[158:161], v[174:177], v[60:63]
	v_mfma_f32_16x16x32_bf16 v[56:59], v[158:161], v[182:185], v[56:59]
	v_mfma_f32_16x16x32_bf16 v[52:55], v[158:161], v[186:189], v[52:55]
	v_mfma_f32_16x16x32_bf16 v[48:51], v[158:161], v[190:193], v[48:51]
	v_mfma_f32_16x16x32_bf16 v[44:47], v[162:165], v[174:177], v[44:47]
	v_mfma_f32_16x16x32_bf16 v[40:43], v[162:165], v[182:185], v[40:43]
	v_mfma_f32_16x16x32_bf16 v[36:39], v[162:165], v[186:189], v[36:39]
	v_mfma_f32_16x16x32_bf16 v[32:35], v[162:165], v[190:193], v[32:35]
	v_mfma_f32_16x16x32_bf16 v[28:31], v[166:169], v[174:177], v[28:31]
	v_mfma_f32_16x16x32_bf16 v[20:23], v[166:169], v[182:185], v[20:23]
	v_mfma_f32_16x16x32_bf16 v[16:19], v[166:169], v[186:189], v[16:19]
	v_mfma_f32_16x16x32_bf16 v[8:11], v[166:169], v[190:193], v[8:11]
	v_mfma_f32_16x16x32_bf16 v[4:7], v[170:173], v[174:177], v[4:7]
	v_mfma_f32_16x16x32_bf16 v[0:3], v[170:173], v[182:185], v[0:3]
	v_mfma_f32_16x16x32_bf16 v[24:27], v[170:173], v[186:189], v[24:27]
	v_mfma_f32_16x16x32_bf16 v[12:15], v[170:173], v[190:193], v[12:15]
	ds_read_b128 v[158:161], v213 offset:8192
	ds_read_b128 v[162:165], v213 offset:10240
	ds_read_b128 v[166:169], v213 offset:12288
	ds_read_b128 v[170:173], v213 offset:14336
	s_waitcnt lgkmcnt(4)
	v_mfma_f32_16x16x32_bf16 v[124:127], v[142:145], v[194:197], v[124:127]
	v_mfma_f32_16x16x32_bf16 v[120:123], v[142:145], v[198:201], v[120:123]
	v_mfma_f32_16x16x32_bf16 v[116:119], v[142:145], v[202:205], v[116:119]
	v_mfma_f32_16x16x32_bf16 v[112:115], v[142:145], v[206:209], v[112:115]
	v_mfma_f32_16x16x32_bf16 v[108:111], v[146:149], v[194:197], v[108:111]
	v_mfma_f32_16x16x32_bf16 v[104:107], v[146:149], v[198:201], v[104:107]
	v_mfma_f32_16x16x32_bf16 v[100:103], v[146:149], v[202:205], v[100:103]
	v_mfma_f32_16x16x32_bf16 v[96:99], v[146:149], v[206:209], v[96:99]
	v_mfma_f32_16x16x32_bf16 v[92:95], v[150:153], v[194:197], v[92:95]
	v_mfma_f32_16x16x32_bf16 v[88:91], v[150:153], v[198:201], v[88:91]
	v_mfma_f32_16x16x32_bf16 v[84:87], v[150:153], v[202:205], v[84:87]
	v_mfma_f32_16x16x32_bf16 v[80:83], v[150:153], v[206:209], v[80:83]
	v_mfma_f32_16x16x32_bf16 v[76:79], v[154:157], v[194:197], v[76:79]
	v_mfma_f32_16x16x32_bf16 v[72:75], v[154:157], v[198:201], v[72:75]
	v_mfma_f32_16x16x32_bf16 v[68:71], v[154:157], v[202:205], v[68:71]
	v_mfma_f32_16x16x32_bf16 v[64:67], v[154:157], v[206:209], v[64:67]
	s_add_u32 s50, s50, 0x80
	s_addc_u32 s51, s51, 0
	s_add_i32 s49, s49, 1
	s_branch .Lg1_top

.Lg2_top:
	s_waitcnt lgkmcnt(0)
	s_waitcnt vmcnt(0)
	s_barrier
	s_xor_b32 s62, s62, 0x10000
	s_mov_b32 m0, s62
	s_add_u32 s50, s48, s12
	s_addc_u32 s51, s49, s13
	global_load_lds_dwordx4 v178, s[50:51]
	ds_read_b128 v[146:149], v180
	ds_read_b128 v[150:153], v180 offset:2048
	ds_read_b128 v[154:157], v180 offset:4096
	ds_read_b128 v[158:161], v180 offset:6144
	ds_read_b128 v[182:185], v215 offset:32768
	ds_read_b128 v[186:189], v215 offset:34816
	ds_read_b128 v[190:193], v215 offset:36864
	ds_read_b128 v[194:197], v215 offset:38912
	v_mfma_f32_16x16x32_bf16 v[60:63], v[162:165], v[198:201], v[60:63]
	v_mfma_f32_16x16x32_bf16 v[56:59], v[162:165], v[202:205], v[56:59]
	s_add_u32 m0, s62, 0x2000
	s_add_u32 s50, s48, s14
	s_addc_u32 s51, s49, s15
	global_load_lds_dwordx4 v178, s[50:51]
	v_mfma_f32_16x16x32_bf16 v[52:55], v[162:165], v[206:209], v[52:55]
	v_mfma_f32_16x16x32_bf16 v[44:47], v[162:165], v[210:213], v[44:47]
	s_add_u32 m0, s62, 0x4000
	s_add_u32 s50, s48, s16
	s_addc_u32 s51, s49, s17
	global_load_lds_dwordx4 v178, s[50:51]
	v_mfma_f32_16x16x32_bf16 v[36:39], v[166:169], v[198:201], v[36:39]
	v_mfma_f32_16x16x32_bf16 v[32:35], v[166:169], v[202:205], v[32:35]
	s_add_u32 m0, s62, 0x6000
	s_add_u32 s50, s48, s18
	s_addc_u32 s51, s49, s19
	global_load_lds_dwordx4 v178, s[50:51]
	v_mfma_f32_16x16x32_bf16 v[28:31], v[166:169], v[206:209], v[28:31]
	v_mfma_f32_16x16x32_bf16 v[24:27], v[166:169], v[210:213], v[24:27]
	s_add_u32 m0, s62, 0x8000
	s_add_u32 s50, s48, s22
	s_addc_u32 s51, s49, s23
	global_load_lds_dwordx4 v179, s[50:51]
	v_mfma_f32_16x16x32_bf16 v[20:23], v[170:173], v[198:201], v[20:23]
	v_mfma_f32_16x16x32_bf16 v[16:19], v[170:173], v[202:205], v[16:19]
	s_add_u32 m0, s62, 0xa000
	s_add_u32 s50, s48, s36
	s_addc_u32 s51, s49, s37
	global_load_lds_dwordx4 v179, s[50:51]
	v_mfma_f32_16x16x32_bf16 v[12:15], v[170:173], v[206:209], v[12:15]
	v_mfma_f32_16x16x32_bf16 v[8:11], v[170:173], v[210:213], v[8:11]
	s_add_u32 m0, s62, 0xc000
	s_add_u32 s50, s48, s40
	s_addc_u32 s51, s49, s41
	global_load_lds_dwordx4 v179, s[50:51]
	v_mfma_f32_16x16x32_bf16 v[4:7], v[174:177], v[198:201], v[4:7]
	v_mfma_f32_16x16x32_bf16 v[0:3], v[174:177], v[202:205], v[0:3]
	s_add_u32 m0, s62, 0xe000
	s_add_u32 s50, s48, s42
	s_addc_u32 s51, s49, s43
	global_load_lds_dwordx4 v179, s[50:51]
	v_mfma_f32_16x16x32_bf16 v[48:51], v[174:177], v[206:209], v[48:51]
	v_mfma_f32_16x16x32_bf16 v[40:43], v[174:177], v[210:213], v[40:43]
.Lg2_entry:
	ds_read_b128 v[162:165], v180 offset:8192
	ds_read_b128 v[166:169], v180 offset:10240
	ds_read_b128 v[170:173], v180 offset:12288
	ds_read_b128 v[174:177], v180 offset:14336
	s_waitcnt lgkmcnt(4)
	v_mfma_f32_16x16x32_bf16 v[124:127], v[146:149], v[182:185], v[124:127]
	v_mfma_f32_16x16x32_bf16 v[120:123], v[146:149], v[186:189], v[120:123]
	v_mfma_f32_16x16x32_bf16 v[116:119], v[146:149], v[190:193], v[116:119]
	v_mfma_f32_16x16x32_bf16 v[112:115], v[146:149], v[194:197], v[112:115]
	v_mfma_f32_16x16x32_bf16 v[108:111], v[150:153], v[182:185], v[108:111]
	v_mfma_f32_16x16x32_bf16 v[104:107], v[150:153], v[186:189], v[104:107]
	v_mfma_f32_16x16x32_bf16 v[100:103], v[150:153], v[190:193], v[100:103]
	v_mfma_f32_16x16x32_bf16 v[96:99], v[150:153], v[194:197], v[96:99]
	v_mfma_f32_16x16x32_bf16 v[92:95], v[154:157], v[182:185], v[92:95]
	v_mfma_f32_16x16x32_bf16 v[88:91], v[154:157], v[186:189], v[88:91]
	v_mfma_f32_16x16x32_bf16 v[84:87], v[154:157], v[190:193], v[84:87]
	v_mfma_f32_16x16x32_bf16 v[80:83], v[154:157], v[194:197], v[80:83]
	v_mfma_f32_16x16x32_bf16 v[76:79], v[158:161], v[182:185], v[76:79]
	v_mfma_f32_16x16x32_bf16 v[72:75], v[158:161], v[186:189], v[72:75]
	v_mfma_f32_16x16x32_bf16 v[68:71], v[158:161], v[190:193], v[68:71]
	v_mfma_f32_16x16x32_bf16 v[64:67], v[158:161], v[194:197], v[64:67]
	ds_read_b128 v[146:149], v214
	ds_read_b128 v[150:153], v214 offset:2048
	ds_read_b128 v[154:157], v214 offset:4096
	ds_read_b128 v[158:161], v214 offset:6144
	ds_read_b128 v[198:201], v216 offset:32768
	ds_read_b128 v[202:205], v216 offset:34816
	ds_read_b128 v[206:209], v216 offset:36864
	ds_read_b128 v[210:213], v216 offset:38912
	s_waitcnt lgkmcnt(8)
	v_mfma_f32_16x16x32_bf16 v[60:63], v[162:165], v[182:185], v[60:63]
	v_mfma_f32_16x16x32_bf16 v[56:59], v[162:165], v[186:189], v[56:59]
	v_mfma_f32_16x16x32_bf16 v[52:55], v[162:165], v[190:193], v[52:55]
	v_mfma_f32_16x16x32_bf16 v[44:47], v[162:165], v[194:197], v[44:47]
	v_mfma_f32_16x16x32_bf16 v[36:39], v[166:169], v[182:185], v[36:39]
	v_mfma_f32_16x16x32_bf16 v[32:35], v[166:169], v[186:189], v[32:35]
	v_mfma_f32_16x16x32_bf16 v[28:31], v[166:169], v[190:193], v[28:31]
	v_mfma_f32_16x16x32_bf16 v[24:27], v[166:169], v[194:197], v[24:27]
	v_mfma_f32_16x16x32_bf16 v[20:23], v[170:173], v[182:185], v[20:23]
	v_mfma_f32_16x16x32_bf16 v[16:19], v[170:173], v[186:189], v[16:19]
	v_mfma_f32_16x16x32_bf16 v[12:15], v[170:173], v[190:193], v[12:15]
	v_mfma_f32_16x16x32_bf16 v[8:11], v[170:173], v[194:197], v[8:11]
	v_mfma_f32_16x16x32_bf16 v[4:7], v[174:177], v[182:185], v[4:7]
	v_mfma_f32_16x16x32_bf16 v[0:3], v[174:177], v[186:189], v[0:3]
	v_mfma_f32_16x16x32_bf16 v[48:51], v[174:177], v[190:193], v[48:51]
	v_mfma_f32_16x16x32_bf16 v[40:43], v[174:177], v[194:197], v[40:43]
	ds_read_b128 v[162:165], v214 offset:8192
	ds_read_b128 v[166:169], v214 offset:10240
	ds_read_b128 v[170:173], v214 offset:12288
	ds_read_b128 v[174:177], v214 offset:14336
	s_waitcnt lgkmcnt(4)
	v_mfma_f32_16x16x32_bf16 v[124:127], v[146:149], v[198:201], v[124:127]
	v_mfma_f32_16x16x32_bf16 v[120:123], v[146:149], v[202:205], v[120:123]
	v_mfma_f32_16x16x32_bf16 v[116:119], v[146:149], v[206:209], v[116:119]
	v_mfma_f32_16x16x32_bf16 v[112:115], v[146:149], v[210:213], v[112:115]
	v_mfma_f32_16x16x32_bf16 v[108:111], v[150:153], v[198:201], v[108:111]
	v_mfma_f32_16x16x32_bf16 v[104:107], v[150:153], v[202:205], v[104:107]
	v_mfma_f32_16x16x32_bf16 v[100:103], v[150:153], v[206:209], v[100:103]
	v_mfma_f32_16x16x32_bf16 v[96:99], v[150:153], v[210:213], v[96:99]
	v_mfma_f32_16x16x32_bf16 v[92:95], v[154:157], v[198:201], v[92:95]
	v_mfma_f32_16x16x32_bf16 v[88:91], v[154:157], v[202:205], v[88:91]
	v_mfma_f32_16x16x32_bf16 v[84:87], v[154:157], v[206:209], v[84:87]
	v_mfma_f32_16x16x32_bf16 v[80:83], v[154:157], v[210:213], v[80:83]
	v_mfma_f32_16x16x32_bf16 v[76:79], v[158:161], v[198:201], v[76:79]
	v_mfma_f32_16x16x32_bf16 v[72:75], v[158:161], v[202:205], v[72:75]
	v_mfma_f32_16x16x32_bf16 v[68:71], v[158:161], v[206:209], v[68:71]
	v_mfma_f32_16x16x32_bf16 v[64:67], v[158:161], v[210:213], v[64:67]
	s_add_u32 s48, s48, 0x80
	s_addc_u32 s49, s49, 0
	s_add_i32 s47, s47, 1
	s_cmp_lt_u32 s47, 15
	s_cbranch_scc0 .Lg2_last
	s_waitcnt lgkmcnt(0)
	s_waitcnt vmcnt(0)
	s_barrier
	s_xor_b32 s62, s62, 0x10000
	s_mov_b32 m0, s62
	s_add_u32 s50, s48, s12
	s_addc_u32 s51, s49, s13
	global_load_lds_dwordx4 v178, s[50:51]
	ds_read_b128 v[146:149], v217
	ds_read_b128 v[150:153], v217 offset:2048
	ds_read_b128 v[154:157], v217 offset:4096
	ds_read_b128 v[158:161], v217 offset:6144
	ds_read_b128 v[182:185], v219 offset:32768
	ds_read_b128 v[186:189], v219 offset:34816
	ds_read_b128 v[190:193], v219 offset:36864
	ds_read_b128 v[194:197], v219 offset:38912
	v_mfma_f32_16x16x32_bf16 v[60:63], v[162:165], v[198:201], v[60:63]
	v_mfma_f32_16x16x32_bf16 v[56:59], v[162:165], v[202:205], v[56:59]
	s_add_u32 m0, s62, 0x2000
	s_add_u32 s50, s48, s14
	s_addc_u32 s51, s49, s15
	global_load_lds_dwordx4 v178, s[50:51]
	v_mfma_f32_16x16x32_bf16 v[52:55], v[162:165], v[206:209], v[52:55]
	v_mfma_f32_16x16x32_bf16 v[44:47], v[162:165], v[210:213], v[44:47]
	s_add_u32 m0, s62, 0x4000
	s_add_u32 s50, s48, s16
	s_addc_u32 s51, s49, s17
	global_load_lds_dwordx4 v178, s[50:51]
	v_mfma_f32_16x16x32_bf16 v[36:39], v[166:169], v[198:201], v[36:39]
	v_mfma_f32_16x16x32_bf16 v[32:35], v[166:169], v[202:205], v[32:35]
	s_add_u32 m0, s62, 0x6000
	s_add_u32 s50, s48, s18
	s_addc_u32 s51, s49, s19
	global_load_lds_dwordx4 v178, s[50:51]
	v_mfma_f32_16x16x32_bf16 v[28:31], v[166:169], v[206:209], v[28:31]
	v_mfma_f32_16x16x32_bf16 v[24:27], v[166:169], v[210:213], v[24:27]
	s_add_u32 m0, s62, 0x8000
	s_add_u32 s50, s48, s22
	s_addc_u32 s51, s49, s23
	global_load_lds_dwordx4 v179, s[50:51]
	v_mfma_f32_16x16x32_bf16 v[20:23], v[170:173], v[198:201], v[20:23]
	v_mfma_f32_16x16x32_bf16 v[16:19], v[170:173], v[202:205], v[16:19]
	s_add_u32 m0, s62, 0xa000
	s_add_u32 s50, s48, s36
	s_addc_u32 s51, s49, s37
	global_load_lds_dwordx4 v179, s[50:51]
	v_mfma_f32_16x16x32_bf16 v[12:15], v[170:173], v[206:209], v[12:15]
	v_mfma_f32_16x16x32_bf16 v[8:11], v[170:173], v[210:213], v[8:11]
	s_add_u32 m0, s62, 0xc000
	s_add_u32 s50, s48, s40
	s_addc_u32 s51, s49, s41
	global_load_lds_dwordx4 v179, s[50:51]
	v_mfma_f32_16x16x32_bf16 v[4:7], v[174:177], v[198:201], v[4:7]
	v_mfma_f32_16x16x32_bf16 v[0:3], v[174:177], v[202:205], v[0:3]
	s_add_u32 m0, s62, 0xe000
	s_add_u32 s50, s48, s42
	s_addc_u32 s51, s49, s43
	global_load_lds_dwordx4 v179, s[50:51]
	v_mfma_f32_16x16x32_bf16 v[48:51], v[174:177], v[206:209], v[48:51]
	v_mfma_f32_16x16x32_bf16 v[40:43], v[174:177], v[210:213], v[40:43]
	ds_read_b128 v[162:165], v217 offset:8192
	ds_read_b128 v[166:169], v217 offset:10240
	ds_read_b128 v[170:173], v217 offset:12288
	ds_read_b128 v[174:177], v217 offset:14336
	s_waitcnt lgkmcnt(4)
	v_mfma_f32_16x16x32_bf16 v[124:127], v[146:149], v[182:185], v[124:127]
	v_mfma_f32_16x16x32_bf16 v[120:123], v[146:149], v[186:189], v[120:123]
	v_mfma_f32_16x16x32_bf16 v[116:119], v[146:149], v[190:193], v[116:119]
	v_mfma_f32_16x16x32_bf16 v[112:115], v[146:149], v[194:197], v[112:115]
	v_mfma_f32_16x16x32_bf16 v[108:111], v[150:153], v[182:185], v[108:111]
	v_mfma_f32_16x16x32_bf16 v[104:107], v[150:153], v[186:189], v[104:107]
	v_mfma_f32_16x16x32_bf16 v[100:103], v[150:153], v[190:193], v[100:103]
	v_mfma_f32_16x16x32_bf16 v[96:99], v[150:153], v[194:197], v[96:99]
	v_mfma_f32_16x16x32_bf16 v[92:95], v[154:157], v[182:185], v[92:95]
	v_mfma_f32_16x16x32_bf16 v[88:91], v[154:157], v[186:189], v[88:91]
	v_mfma_f32_16x16x32_bf16 v[84:87], v[154:157], v[190:193], v[84:87]
	v_mfma_f32_16x16x32_bf16 v[80:83], v[154:157], v[194:197], v[80:83]
	v_mfma_f32_16x16x32_bf16 v[76:79], v[158:161], v[182:185], v[76:79]
	v_mfma_f32_16x16x32_bf16 v[72:75], v[158:161], v[186:189], v[72:75]
	v_mfma_f32_16x16x32_bf16 v[68:71], v[158:161], v[190:193], v[68:71]
	v_mfma_f32_16x16x32_bf16 v[64:67], v[158:161], v[194:197], v[64:67]
	ds_read_b128 v[146:149], v218
	ds_read_b128 v[150:153], v218 offset:2048
	ds_read_b128 v[154:157], v218 offset:4096
	ds_read_b128 v[158:161], v218 offset:6144
	ds_read_b128 v[198:201], v220 offset:32768
	ds_read_b128 v[202:205], v220 offset:34816
	ds_read_b128 v[206:209], v220 offset:36864
	ds_read_b128 v[210:213], v220 offset:38912
	s_waitcnt lgkmcnt(8)
	v_mfma_f32_16x16x32_bf16 v[60:63], v[162:165], v[182:185], v[60:63]
	v_mfma_f32_16x16x32_bf16 v[56:59], v[162:165], v[186:189], v[56:59]
	v_mfma_f32_16x16x32_bf16 v[52:55], v[162:165], v[190:193], v[52:55]
	v_mfma_f32_16x16x32_bf16 v[44:47], v[162:165], v[194:197], v[44:47]
	v_mfma_f32_16x16x32_bf16 v[36:39], v[166:169], v[182:185], v[36:39]
	v_mfma_f32_16x16x32_bf16 v[32:35], v[166:169], v[186:189], v[32:35]
	v_mfma_f32_16x16x32_bf16 v[28:31], v[166:169], v[190:193], v[28:31]
	v_mfma_f32_16x16x32_bf16 v[24:27], v[166:169], v[194:197], v[24:27]
	v_mfma_f32_16x16x32_bf16 v[20:23], v[170:173], v[182:185], v[20:23]
	v_mfma_f32_16x16x32_bf16 v[16:19], v[170:173], v[186:189], v[16:19]
	v_mfma_f32_16x16x32_bf16 v[12:15], v[170:173], v[190:193], v[12:15]
	v_mfma_f32_16x16x32_bf16 v[8:11], v[170:173], v[194:197], v[8:11]
	v_mfma_f32_16x16x32_bf16 v[4:7], v[174:177], v[182:185], v[4:7]
	v_mfma_f32_16x16x32_bf16 v[0:3], v[174:177], v[186:189], v[0:3]
	v_mfma_f32_16x16x32_bf16 v[48:51], v[174:177], v[190:193], v[48:51]
	v_mfma_f32_16x16x32_bf16 v[40:43], v[174:177], v[194:197], v[40:43]
	ds_read_b128 v[162:165], v218 offset:8192
	ds_read_b128 v[166:169], v218 offset:10240
	ds_read_b128 v[170:173], v218 offset:12288
	ds_read_b128 v[174:177], v218 offset:14336
	s_waitcnt lgkmcnt(4)
	v_mfma_f32_16x16x32_bf16 v[124:127], v[146:149], v[198:201], v[124:127]
	v_mfma_f32_16x16x32_bf16 v[120:123], v[146:149], v[202:205], v[120:123]
	v_mfma_f32_16x16x32_bf16 v[116:119], v[146:149], v[206:209], v[116:119]
	v_mfma_f32_16x16x32_bf16 v[112:115], v[146:149], v[210:213], v[112:115]
	v_mfma_f32_16x16x32_bf16 v[108:111], v[150:153], v[198:201], v[108:111]
	v_mfma_f32_16x16x32_bf16 v[104:107], v[150:153], v[202:205], v[104:107]
	v_mfma_f32_16x16x32_bf16 v[100:103], v[150:153], v[206:209], v[100:103]
	v_mfma_f32_16x16x32_bf16 v[96:99], v[150:153], v[210:213], v[96:99]
	v_mfma_f32_16x16x32_bf16 v[92:95], v[154:157], v[198:201], v[92:95]
	v_mfma_f32_16x16x32_bf16 v[88:91], v[154:157], v[202:205], v[88:91]
	v_mfma_f32_16x16x32_bf16 v[84:87], v[154:157], v[206:209], v[84:87]
	v_mfma_f32_16x16x32_bf16 v[80:83], v[154:157], v[210:213], v[80:83]
	v_mfma_f32_16x16x32_bf16 v[76:79], v[158:161], v[198:201], v[76:79]
	v_mfma_f32_16x16x32_bf16 v[72:75], v[158:161], v[202:205], v[72:75]
	v_mfma_f32_16x16x32_bf16 v[68:71], v[158:161], v[206:209], v[68:71]
	v_mfma_f32_16x16x32_bf16 v[64:67], v[158:161], v[210:213], v[64:67]
	s_add_u32 s48, s48, 0x80
	s_addc_u32 s49, s49, 0
	s_add_i32 s47, s47, 1
	s_branch .Lg2_top

.Lg5_top:
	s_waitcnt lgkmcnt(0)
	s_waitcnt vmcnt(0)
	s_barrier
	s_xor_b32 s87, s87, 0x10000
	s_mov_b32 m0, s87
	s_add_u32 s70, s68, 0x4000080
	s_addc_u32 s71, s69, 0
	global_load_lds_dwordx4 v242, s[70:71]
	ds_read_b128 v[176:179], v180
	ds_read_b128 v[182:185], v180 offset:2048
	ds_read_b128 v[186:189], v180 offset:4096
	ds_read_b128 v[190:193], v180 offset:6144
	ds_read_b128 v[210:213], v245 offset:32768
	ds_read_b128 v[214:217], v245 offset:34816
	ds_read_b128 v[218:221], v245 offset:36864
	ds_read_b128 v[222:225], v245 offset:38912
	v_mfma_f32_16x16x32_bf16 v[60:63], v[194:197], v[226:229], v[60:63]
	v_mfma_f32_16x16x32_bf16 v[56:59], v[194:197], v[230:233], v[56:59]
	s_add_u32 m0, s87, 0x2000
	s_add_u32 s70, s68, 0x4020080
	s_addc_u32 s71, s69, 0
	global_load_lds_dwordx4 v242, s[70:71]
	v_mfma_f32_16x16x32_bf16 v[52:55], v[194:197], v[234:237], v[52:55]
	v_mfma_f32_16x16x32_bf16 v[48:51], v[194:197], v[238:241], v[48:51]
	s_add_u32 m0, s87, 0x4000
	s_add_u32 s70, s68, 0x4040080
	s_addc_u32 s71, s69, 0
	global_load_lds_dwordx4 v242, s[70:71]
	v_mfma_f32_16x16x32_bf16 v[44:47], v[198:201], v[226:229], v[44:47]
	v_mfma_f32_16x16x32_bf16 v[40:43], v[198:201], v[230:233], v[40:43]
	s_add_u32 m0, s87, 0x6000
	s_add_u32 s70, s68, s14
	s_addc_u32 s71, s69, s15
	global_load_lds_dwordx4 v242, s[70:71]
	v_mfma_f32_16x16x32_bf16 v[36:39], v[198:201], v[234:237], v[36:39]
	v_mfma_f32_16x16x32_bf16 v[32:35], v[198:201], v[238:241], v[32:35]
	s_add_u32 m0, s87, 0x8000
	s_add_u32 s70, s68, s16
	s_addc_u32 s71, s69, s17
	global_load_lds_dwordx4 v243, s[70:71]
	v_mfma_f32_16x16x32_bf16 v[28:31], v[202:205], v[226:229], v[28:31]
	v_mfma_f32_16x16x32_bf16 v[24:27], v[202:205], v[230:233], v[24:27]
	s_add_u32 m0, s87, 0xa000
	s_add_u32 s70, s68, s18
	s_addc_u32 s71, s69, s19
	global_load_lds_dwordx4 v243, s[70:71]
	v_mfma_f32_16x16x32_bf16 v[20:23], v[202:205], v[234:237], v[20:23]
	v_mfma_f32_16x16x32_bf16 v[16:19], v[202:205], v[238:241], v[16:19]
	s_add_u32 m0, s87, 0xc000
	s_add_u32 s70, s68, s22
	s_addc_u32 s71, s69, s23
	global_load_lds_dwordx4 v243, s[70:71]
	v_mfma_f32_16x16x32_bf16 v[8:11], v[206:209], v[226:229], v[8:11]
	v_mfma_f32_16x16x32_bf16 v[0:3], v[206:209], v[230:233], v[0:3]
	s_add_u32 m0, s87, 0xe000
	s_add_u32 s70, s68, s36
	s_addc_u32 s71, s69, s37
	global_load_lds_dwordx4 v243, s[70:71]
	v_mfma_f32_16x16x32_bf16 v[12:15], v[206:209], v[234:237], v[12:15]
	v_mfma_f32_16x16x32_bf16 v[4:7], v[206:209], v[238:241], v[4:7]
.Lg5_entry:
	ds_read_b128 v[194:197], v180 offset:8192
	ds_read_b128 v[198:201], v180 offset:10240
	ds_read_b128 v[202:205], v180 offset:12288
	ds_read_b128 v[206:209], v180 offset:14336
	s_waitcnt lgkmcnt(4)
	v_mfma_f32_16x16x32_bf16 v[124:127], v[176:179], v[210:213], v[124:127]
	v_mfma_f32_16x16x32_bf16 v[120:123], v[176:179], v[214:217], v[120:123]
	v_mfma_f32_16x16x32_bf16 v[116:119], v[176:179], v[218:221], v[116:119]
	v_mfma_f32_16x16x32_bf16 v[112:115], v[176:179], v[222:225], v[112:115]
	v_mfma_f32_16x16x32_bf16 v[108:111], v[182:185], v[210:213], v[108:111]
	v_mfma_f32_16x16x32_bf16 v[104:107], v[182:185], v[214:217], v[104:107]
	v_mfma_f32_16x16x32_bf16 v[100:103], v[182:185], v[218:221], v[100:103]
	v_mfma_f32_16x16x32_bf16 v[96:99], v[182:185], v[222:225], v[96:99]
	v_mfma_f32_16x16x32_bf16 v[92:95], v[186:189], v[210:213], v[92:95]
	v_mfma_f32_16x16x32_bf16 v[88:91], v[186:189], v[214:217], v[88:91]
	v_mfma_f32_16x16x32_bf16 v[84:87], v[186:189], v[218:221], v[84:87]
	v_mfma_f32_16x16x32_bf16 v[80:83], v[186:189], v[222:225], v[80:83]
	v_mfma_f32_16x16x32_bf16 v[76:79], v[190:193], v[210:213], v[76:79]
	v_mfma_f32_16x16x32_bf16 v[72:75], v[190:193], v[214:217], v[72:75]
	v_mfma_f32_16x16x32_bf16 v[68:71], v[190:193], v[218:221], v[68:71]
	v_mfma_f32_16x16x32_bf16 v[64:67], v[190:193], v[222:225], v[64:67]
	ds_read_b128 v[176:179], v244
	ds_read_b128 v[182:185], v244 offset:2048
	ds_read_b128 v[186:189], v244 offset:4096
	ds_read_b128 v[190:193], v244 offset:6144
	ds_read_b128 v[226:229], v246 offset:32768
	ds_read_b128 v[230:233], v246 offset:34816
	ds_read_b128 v[234:237], v246 offset:36864
	ds_read_b128 v[238:241], v246 offset:38912
	s_waitcnt lgkmcnt(8)
	v_mfma_f32_16x16x32_bf16 v[60:63], v[194:197], v[210:213], v[60:63]
	v_mfma_f32_16x16x32_bf16 v[56:59], v[194:197], v[214:217], v[56:59]
	v_mfma_f32_16x16x32_bf16 v[52:55], v[194:197], v[218:221], v[52:55]
	v_mfma_f32_16x16x32_bf16 v[48:51], v[194:197], v[222:225], v[48:51]
	v_mfma_f32_16x16x32_bf16 v[44:47], v[198:201], v[210:213], v[44:47]
	v_mfma_f32_16x16x32_bf16 v[40:43], v[198:201], v[214:217], v[40:43]
	v_mfma_f32_16x16x32_bf16 v[36:39], v[198:201], v[218:221], v[36:39]
	v_mfma_f32_16x16x32_bf16 v[32:35], v[198:201], v[222:225], v[32:35]
	v_mfma_f32_16x16x32_bf16 v[28:31], v[202:205], v[210:213], v[28:31]
	v_mfma_f32_16x16x32_bf16 v[24:27], v[202:205], v[214:217], v[24:27]
	v_mfma_f32_16x16x32_bf16 v[20:23], v[202:205], v[218:221], v[20:23]
	v_mfma_f32_16x16x32_bf16 v[16:19], v[202:205], v[222:225], v[16:19]
	v_mfma_f32_16x16x32_bf16 v[8:11], v[206:209], v[210:213], v[8:11]
	v_mfma_f32_16x16x32_bf16 v[0:3], v[206:209], v[214:217], v[0:3]
	v_mfma_f32_16x16x32_bf16 v[12:15], v[206:209], v[218:221], v[12:15]
	v_mfma_f32_16x16x32_bf16 v[4:7], v[206:209], v[222:225], v[4:7]
	ds_read_b128 v[194:197], v244 offset:8192
	ds_read_b128 v[198:201], v244 offset:10240
	ds_read_b128 v[202:205], v244 offset:12288
	ds_read_b128 v[206:209], v244 offset:14336
	s_waitcnt lgkmcnt(4)
	v_mfma_f32_16x16x32_bf16 v[124:127], v[176:179], v[226:229], v[124:127]
	v_mfma_f32_16x16x32_bf16 v[120:123], v[176:179], v[230:233], v[120:123]
	v_mfma_f32_16x16x32_bf16 v[116:119], v[176:179], v[234:237], v[116:119]
	v_mfma_f32_16x16x32_bf16 v[112:115], v[176:179], v[238:241], v[112:115]
	v_mfma_f32_16x16x32_bf16 v[108:111], v[182:185], v[226:229], v[108:111]
	v_mfma_f32_16x16x32_bf16 v[104:107], v[182:185], v[230:233], v[104:107]
	v_mfma_f32_16x16x32_bf16 v[100:103], v[182:185], v[234:237], v[100:103]
	v_mfma_f32_16x16x32_bf16 v[96:99], v[182:185], v[238:241], v[96:99]
	v_mfma_f32_16x16x32_bf16 v[92:95], v[186:189], v[226:229], v[92:95]
	v_mfma_f32_16x16x32_bf16 v[88:91], v[186:189], v[230:233], v[88:91]
	v_mfma_f32_16x16x32_bf16 v[84:87], v[186:189], v[234:237], v[84:87]
	v_mfma_f32_16x16x32_bf16 v[80:83], v[186:189], v[238:241], v[80:83]
	v_mfma_f32_16x16x32_bf16 v[76:79], v[190:193], v[226:229], v[76:79]
	v_mfma_f32_16x16x32_bf16 v[72:75], v[190:193], v[230:233], v[72:75]
	v_mfma_f32_16x16x32_bf16 v[68:71], v[190:193], v[234:237], v[68:71]
	v_mfma_f32_16x16x32_bf16 v[64:67], v[190:193], v[238:241], v[64:67]
	s_add_u32 s68, s68, 0x80
	s_addc_u32 s69, s69, 0
	s_add_i32 s86, s86, 1
	s_cmp_lt_u32 s86, 15
	s_cbranch_scc0 .Lg5_last
	s_waitcnt lgkmcnt(0)
	s_waitcnt vmcnt(0)
	s_barrier
	s_xor_b32 s87, s87, 0x10000
	s_mov_b32 m0, s87
	s_add_u32 s70, s68, 0x4000080
	s_addc_u32 s71, s69, 0
	global_load_lds_dwordx4 v242, s[70:71]
	ds_read_b128 v[176:179], v247
	ds_read_b128 v[182:185], v247 offset:2048
	ds_read_b128 v[186:189], v247 offset:4096
	ds_read_b128 v[190:193], v247 offset:6144
	ds_read_b128 v[210:213], v249 offset:32768
	ds_read_b128 v[214:217], v249 offset:34816
	ds_read_b128 v[218:221], v249 offset:36864
	ds_read_b128 v[222:225], v249 offset:38912
	v_mfma_f32_16x16x32_bf16 v[60:63], v[194:197], v[226:229], v[60:63]
	v_mfma_f32_16x16x32_bf16 v[56:59], v[194:197], v[230:233], v[56:59]
	s_add_u32 m0, s87, 0x2000
	s_add_u32 s70, s68, 0x4020080
	s_addc_u32 s71, s69, 0
	global_load_lds_dwordx4 v242, s[70:71]
	v_mfma_f32_16x16x32_bf16 v[52:55], v[194:197], v[234:237], v[52:55]
	v_mfma_f32_16x16x32_bf16 v[48:51], v[194:197], v[238:241], v[48:51]
	s_add_u32 m0, s87, 0x4000
	s_add_u32 s70, s68, 0x4040080
	s_addc_u32 s71, s69, 0
	global_load_lds_dwordx4 v242, s[70:71]
	v_mfma_f32_16x16x32_bf16 v[44:47], v[198:201], v[226:229], v[44:47]
	v_mfma_f32_16x16x32_bf16 v[40:43], v[198:201], v[230:233], v[40:43]
	s_add_u32 m0, s87, 0x6000
	s_add_u32 s70, s68, s14
	s_addc_u32 s71, s69, s15
	global_load_lds_dwordx4 v242, s[70:71]
	v_mfma_f32_16x16x32_bf16 v[36:39], v[198:201], v[234:237], v[36:39]
	v_mfma_f32_16x16x32_bf16 v[32:35], v[198:201], v[238:241], v[32:35]
	s_add_u32 m0, s87, 0x8000
	s_add_u32 s70, s68, s16
	s_addc_u32 s71, s69, s17
	global_load_lds_dwordx4 v243, s[70:71]
	v_mfma_f32_16x16x32_bf16 v[28:31], v[202:205], v[226:229], v[28:31]
	v_mfma_f32_16x16x32_bf16 v[24:27], v[202:205], v[230:233], v[24:27]
	s_add_u32 m0, s87, 0xa000
	s_add_u32 s70, s68, s18
	s_addc_u32 s71, s69, s19
	global_load_lds_dwordx4 v243, s[70:71]
	v_mfma_f32_16x16x32_bf16 v[20:23], v[202:205], v[234:237], v[20:23]
	v_mfma_f32_16x16x32_bf16 v[16:19], v[202:205], v[238:241], v[16:19]
	s_add_u32 m0, s87, 0xc000
	s_add_u32 s70, s68, s22
	s_addc_u32 s71, s69, s23
	global_load_lds_dwordx4 v243, s[70:71]
	v_mfma_f32_16x16x32_bf16 v[8:11], v[206:209], v[226:229], v[8:11]
	v_mfma_f32_16x16x32_bf16 v[0:3], v[206:209], v[230:233], v[0:3]
	s_add_u32 m0, s87, 0xe000
	s_add_u32 s70, s68, s36
	s_addc_u32 s71, s69, s37
	global_load_lds_dwordx4 v243, s[70:71]
	v_mfma_f32_16x16x32_bf16 v[12:15], v[206:209], v[234:237], v[12:15]
	v_mfma_f32_16x16x32_bf16 v[4:7], v[206:209], v[238:241], v[4:7]
	ds_read_b128 v[194:197], v247 offset:8192
	ds_read_b128 v[198:201], v247 offset:10240
	ds_read_b128 v[202:205], v247 offset:12288
	ds_read_b128 v[206:209], v247 offset:14336
	s_waitcnt lgkmcnt(4)
	v_mfma_f32_16x16x32_bf16 v[124:127], v[176:179], v[210:213], v[124:127]
	v_mfma_f32_16x16x32_bf16 v[120:123], v[176:179], v[214:217], v[120:123]
	v_mfma_f32_16x16x32_bf16 v[116:119], v[176:179], v[218:221], v[116:119]
	v_mfma_f32_16x16x32_bf16 v[112:115], v[176:179], v[222:225], v[112:115]
	v_mfma_f32_16x16x32_bf16 v[108:111], v[182:185], v[210:213], v[108:111]
	v_mfma_f32_16x16x32_bf16 v[104:107], v[182:185], v[214:217], v[104:107]
	v_mfma_f32_16x16x32_bf16 v[100:103], v[182:185], v[218:221], v[100:103]
	v_mfma_f32_16x16x32_bf16 v[96:99], v[182:185], v[222:225], v[96:99]
	v_mfma_f32_16x16x32_bf16 v[92:95], v[186:189], v[210:213], v[92:95]
	v_mfma_f32_16x16x32_bf16 v[88:91], v[186:189], v[214:217], v[88:91]
	v_mfma_f32_16x16x32_bf16 v[84:87], v[186:189], v[218:221], v[84:87]
	v_mfma_f32_16x16x32_bf16 v[80:83], v[186:189], v[222:225], v[80:83]
	v_mfma_f32_16x16x32_bf16 v[76:79], v[190:193], v[210:213], v[76:79]
	v_mfma_f32_16x16x32_bf16 v[72:75], v[190:193], v[214:217], v[72:75]
	v_mfma_f32_16x16x32_bf16 v[68:71], v[190:193], v[218:221], v[68:71]
	v_mfma_f32_16x16x32_bf16 v[64:67], v[190:193], v[222:225], v[64:67]
	ds_read_b128 v[176:179], v248
	ds_read_b128 v[182:185], v248 offset:2048
	ds_read_b128 v[186:189], v248 offset:4096
	ds_read_b128 v[190:193], v248 offset:6144
	ds_read_b128 v[226:229], v250 offset:32768
	ds_read_b128 v[230:233], v250 offset:34816
	ds_read_b128 v[234:237], v250 offset:36864
	ds_read_b128 v[238:241], v250 offset:38912
	s_waitcnt lgkmcnt(8)
	v_mfma_f32_16x16x32_bf16 v[60:63], v[194:197], v[210:213], v[60:63]
	v_mfma_f32_16x16x32_bf16 v[56:59], v[194:197], v[214:217], v[56:59]
	v_mfma_f32_16x16x32_bf16 v[52:55], v[194:197], v[218:221], v[52:55]
	v_mfma_f32_16x16x32_bf16 v[48:51], v[194:197], v[222:225], v[48:51]
	v_mfma_f32_16x16x32_bf16 v[44:47], v[198:201], v[210:213], v[44:47]
	v_mfma_f32_16x16x32_bf16 v[40:43], v[198:201], v[214:217], v[40:43]
	v_mfma_f32_16x16x32_bf16 v[36:39], v[198:201], v[218:221], v[36:39]
	v_mfma_f32_16x16x32_bf16 v[32:35], v[198:201], v[222:225], v[32:35]
	v_mfma_f32_16x16x32_bf16 v[28:31], v[202:205], v[210:213], v[28:31]
	v_mfma_f32_16x16x32_bf16 v[24:27], v[202:205], v[214:217], v[24:27]
	v_mfma_f32_16x16x32_bf16 v[20:23], v[202:205], v[218:221], v[20:23]
	v_mfma_f32_16x16x32_bf16 v[16:19], v[202:205], v[222:225], v[16:19]
	v_mfma_f32_16x16x32_bf16 v[8:11], v[206:209], v[210:213], v[8:11]
	v_mfma_f32_16x16x32_bf16 v[0:3], v[206:209], v[214:217], v[0:3]
	v_mfma_f32_16x16x32_bf16 v[12:15], v[206:209], v[218:221], v[12:15]
	v_mfma_f32_16x16x32_bf16 v[4:7], v[206:209], v[222:225], v[4:7]
	ds_read_b128 v[194:197], v248 offset:8192
	ds_read_b128 v[198:201], v248 offset:10240
	ds_read_b128 v[202:205], v248 offset:12288
	ds_read_b128 v[206:209], v248 offset:14336
	s_waitcnt lgkmcnt(4)
	v_mfma_f32_16x16x32_bf16 v[124:127], v[176:179], v[226:229], v[124:127]
	v_mfma_f32_16x16x32_bf16 v[120:123], v[176:179], v[230:233], v[120:123]
	v_mfma_f32_16x16x32_bf16 v[116:119], v[176:179], v[234:237], v[116:119]
	v_mfma_f32_16x16x32_bf16 v[112:115], v[176:179], v[238:241], v[112:115]
	v_mfma_f32_16x16x32_bf16 v[108:111], v[182:185], v[226:229], v[108:111]
	v_mfma_f32_16x16x32_bf16 v[104:107], v[182:185], v[230:233], v[104:107]
	v_mfma_f32_16x16x32_bf16 v[100:103], v[182:185], v[234:237], v[100:103]
	v_mfma_f32_16x16x32_bf16 v[96:99], v[182:185], v[238:241], v[96:99]
	v_mfma_f32_16x16x32_bf16 v[92:95], v[186:189], v[226:229], v[92:95]
	v_mfma_f32_16x16x32_bf16 v[88:91], v[186:189], v[230:233], v[88:91]
	v_mfma_f32_16x16x32_bf16 v[84:87], v[186:189], v[234:237], v[84:87]
	v_mfma_f32_16x16x32_bf16 v[80:83], v[186:189], v[238:241], v[80:83]
	v_mfma_f32_16x16x32_bf16 v[76:79], v[190:193], v[226:229], v[76:79]
	v_mfma_f32_16x16x32_bf16 v[72:75], v[190:193], v[230:233], v[72:75]
	v_mfma_f32_16x16x32_bf16 v[68:71], v[190:193], v[234:237], v[68:71]
	v_mfma_f32_16x16x32_bf16 v[64:67], v[190:193], v[238:241], v[64:67]
	s_add_u32 s68, s68, 0x80
	s_addc_u32 s69, s69, 0
	s_add_i32 s86, s86, 1
	s_branch .Lg5_top

.Lg6_top:
	s_waitcnt lgkmcnt(0)
	s_waitcnt vmcnt(0)
	s_barrier
	v_xor_b32_e32 v180, 0x10000, v180
	v_xor_b32_e32 v249, 0x10000, v249
	v_xor_b32_e32 v248, 0x10000, v248
	v_xor_b32_e32 v250, 0x10000, v250
	s_xor_b32 s69, s69, 0x10000
	s_mov_b32 m0, s69
	s_add_u32 s66, s64, s44
	s_addc_u32 s67, s65, s45
	global_load_lds_dwordx4 v246, s[66:67]
	ds_read_b128 v[182:185], v180
	ds_read_b128 v[186:189], v180 offset:2048
	ds_read_b128 v[190:193], v180 offset:4096
	ds_read_b128 v[194:197], v180 offset:6144
	ds_read_b128 v[214:217], v249 offset:32768
	ds_read_b128 v[218:221], v249 offset:34816
	ds_read_b128 v[222:225], v249 offset:36864
	ds_read_b128 v[226:229], v249 offset:38912
	v_mfma_f32_16x16x32_bf16 v[60:63], v[198:201], v[230:233], v[60:63]
	v_mfma_f32_16x16x32_bf16 v[56:59], v[198:201], v[234:237], v[56:59]
	s_add_u32 m0, s69, 0x2000
	s_add_u32 s66, s64, s46
	s_addc_u32 s67, s65, s47
	global_load_lds_dwordx4 v246, s[66:67]
	v_mfma_f32_16x16x32_bf16 v[52:55], v[198:201], v[238:241], v[52:55]
	v_mfma_f32_16x16x32_bf16 v[48:51], v[198:201], v[242:245], v[48:51]
	s_add_u32 m0, s69, 0x4000
	s_add_u32 s66, s64, s48
	s_addc_u32 s67, s65, s49
	global_load_lds_dwordx4 v246, s[66:67]
	v_mfma_f32_16x16x32_bf16 v[44:47], v[202:205], v[230:233], v[44:47]
	v_mfma_f32_16x16x32_bf16 v[40:43], v[202:205], v[234:237], v[40:43]
	s_add_u32 m0, s69, 0x6000
	s_add_u32 s66, s64, s50
	s_addc_u32 s67, s65, s51
	global_load_lds_dwordx4 v246, s[66:67]
	v_mfma_f32_16x16x32_bf16 v[36:39], v[202:205], v[238:241], v[36:39]
	v_mfma_f32_16x16x32_bf16 v[32:35], v[202:205], v[242:245], v[32:35]
	s_add_u32 m0, s69, 0x8000
	s_add_u32 s66, s64, s52
	s_addc_u32 s67, s65, s53
	global_load_lds_dwordx4 v247, s[66:67]
	v_mfma_f32_16x16x32_bf16 v[28:31], v[206:209], v[230:233], v[28:31]
	v_mfma_f32_16x16x32_bf16 v[24:27], v[206:209], v[234:237], v[24:27]
	s_add_u32 m0, s69, 0xa000
	s_add_u32 s66, s64, s54
	s_addc_u32 s67, s65, s55
	global_load_lds_dwordx4 v247, s[66:67]
	v_mfma_f32_16x16x32_bf16 v[20:23], v[206:209], v[238:241], v[20:23]
	v_mfma_f32_16x16x32_bf16 v[16:19], v[206:209], v[242:245], v[16:19]
	s_add_u32 m0, s69, 0xc000
	s_add_u32 s66, s64, s60
	s_addc_u32 s67, s65, s61
	global_load_lds_dwordx4 v247, s[66:67]
	v_mfma_f32_16x16x32_bf16 v[12:15], v[210:213], v[230:233], v[12:15]
	v_mfma_f32_16x16x32_bf16 v[0:3], v[210:213], v[234:237], v[0:3]
	s_add_u32 m0, s69, 0xe000
	s_add_u32 s66, s64, s62
	s_addc_u32 s67, s65, s63
	global_load_lds_dwordx4 v247, s[66:67]
	v_mfma_f32_16x16x32_bf16 v[8:11], v[210:213], v[238:241], v[8:11]
	v_mfma_f32_16x16x32_bf16 v[4:7], v[210:213], v[242:245], v[4:7]

.Lg7_top:
	s_waitcnt lgkmcnt(0)
	s_waitcnt vmcnt(0)
	s_barrier
	s_xor_b32 s61, s61, 0x10000
	s_mov_b32 m0, s61
	s_add_u32 s50, s48, s14
	s_addc_u32 s51, s49, s15
	global_load_lds_dwordx4 v178, s[50:51]
	ds_read_b128 v[142:145], v141
	ds_read_b128 v[146:149], v141 offset:2048
	ds_read_b128 v[150:153], v141 offset:4096
	ds_read_b128 v[154:157], v141 offset:6144
	ds_read_b128 v[174:177], v210 offset:32768
	ds_read_b128 v[182:185], v210 offset:34816
	ds_read_b128 v[186:189], v210 offset:36864
	ds_read_b128 v[190:193], v210 offset:38912
	v_mfma_f32_16x16x32_bf16 v[60:63], v[158:161], v[194:197], v[60:63]
	v_mfma_f32_16x16x32_bf16 v[56:59], v[158:161], v[198:201], v[56:59]
	s_add_u32 m0, s61, 0x2000
	s_add_u32 s50, s48, s16
	s_addc_u32 s51, s49, s17
	global_load_lds_dwordx4 v178, s[50:51]
	v_mfma_f32_16x16x32_bf16 v[52:55], v[158:161], v[202:205], v[52:55]
	v_mfma_f32_16x16x32_bf16 v[48:51], v[158:161], v[206:209], v[48:51]
	s_add_u32 m0, s61, 0x4000
	s_add_u32 s50, s48, s18
	s_addc_u32 s51, s49, s19
	global_load_lds_dwordx4 v178, s[50:51]
	v_mfma_f32_16x16x32_bf16 v[44:47], v[162:165], v[194:197], v[44:47]
	v_mfma_f32_16x16x32_bf16 v[32:35], v[162:165], v[198:201], v[32:35]
	s_add_u32 m0, s61, 0x6000
	s_add_u32 s50, s48, s22
	s_addc_u32 s51, s49, s23
	global_load_lds_dwordx4 v178, s[50:51]
	v_mfma_f32_16x16x32_bf16 v[28:31], v[162:165], v[202:205], v[28:31]
	v_mfma_f32_16x16x32_bf16 v[24:27], v[162:165], v[206:209], v[24:27]
	s_add_u32 m0, s61, 0x8000
	s_add_u32 s50, s48, s36
	s_addc_u32 s51, s49, s37
	global_load_lds_dwordx4 v179, s[50:51]
	v_mfma_f32_16x16x32_bf16 v[20:23], v[166:169], v[194:197], v[20:23]
	v_mfma_f32_16x16x32_bf16 v[16:19], v[166:169], v[198:201], v[16:19]
	s_add_u32 m0, s61, 0xa000
	s_add_u32 s50, s48, s40
	s_addc_u32 s51, s49, s41
	global_load_lds_dwordx4 v179, s[50:51]
	v_mfma_f32_16x16x32_bf16 v[12:15], v[166:169], v[202:205], v[12:15]
	v_mfma_f32_16x16x32_bf16 v[8:11], v[166:169], v[206:209], v[8:11]
	s_add_u32 m0, s61, 0xc000
	s_add_u32 s50, s48, s42
	s_addc_u32 s51, s49, s43
	global_load_lds_dwordx4 v179, s[50:51]
	v_mfma_f32_16x16x32_bf16 v[4:7], v[170:173], v[194:197], v[4:7]
	v_mfma_f32_16x16x32_bf16 v[0:3], v[170:173], v[198:201], v[0:3]
	s_add_u32 m0, s61, 0xe000
	s_add_u32 s50, s48, s44
	s_addc_u32 s51, s49, s45
	global_load_lds_dwordx4 v179, s[50:51]
	v_mfma_f32_16x16x32_bf16 v[40:43], v[170:173], v[202:205], v[40:43]
	v_mfma_f32_16x16x32_bf16 v[36:39], v[170:173], v[206:209], v[36:39]
.Lg7_entry:
	ds_read_b128 v[158:161], v141 offset:8192
	ds_read_b128 v[162:165], v141 offset:10240
	ds_read_b128 v[166:169], v141 offset:12288
	ds_read_b128 v[170:173], v141 offset:14336
	s_waitcnt lgkmcnt(4)
	v_mfma_f32_16x16x32_bf16 v[124:127], v[142:145], v[174:177], v[124:127]
	v_mfma_f32_16x16x32_bf16 v[120:123], v[142:145], v[182:185], v[120:123]
	v_mfma_f32_16x16x32_bf16 v[116:119], v[142:145], v[186:189], v[116:119]
	v_mfma_f32_16x16x32_bf16 v[112:115], v[142:145], v[190:193], v[112:115]
	v_mfma_f32_16x16x32_bf16 v[108:111], v[146:149], v[174:177], v[108:111]
	v_mfma_f32_16x16x32_bf16 v[104:107], v[146:149], v[182:185], v[104:107]
	v_mfma_f32_16x16x32_bf16 v[100:103], v[146:149], v[186:189], v[100:103]
	v_mfma_f32_16x16x32_bf16 v[96:99], v[146:149], v[190:193], v[96:99]
	v_mfma_f32_16x16x32_bf16 v[92:95], v[150:153], v[174:177], v[92:95]
	v_mfma_f32_16x16x32_bf16 v[88:91], v[150:153], v[182:185], v[88:91]
	v_mfma_f32_16x16x32_bf16 v[84:87], v[150:153], v[186:189], v[84:87]
	v_mfma_f32_16x16x32_bf16 v[80:83], v[150:153], v[190:193], v[80:83]
	v_mfma_f32_16x16x32_bf16 v[76:79], v[154:157], v[174:177], v[76:79]
	v_mfma_f32_16x16x32_bf16 v[72:75], v[154:157], v[182:185], v[72:75]
	v_mfma_f32_16x16x32_bf16 v[68:71], v[154:157], v[186:189], v[68:71]
	v_mfma_f32_16x16x32_bf16 v[64:67], v[154:157], v[190:193], v[64:67]
	ds_read_b128 v[142:145], v180
	ds_read_b128 v[146:149], v180 offset:2048
	ds_read_b128 v[150:153], v180 offset:4096
	ds_read_b128 v[154:157], v180 offset:6144
	ds_read_b128 v[194:197], v211 offset:32768
	ds_read_b128 v[198:201], v211 offset:34816
	ds_read_b128 v[202:205], v211 offset:36864
	ds_read_b128 v[206:209], v211 offset:38912
	s_waitcnt lgkmcnt(8)
	v_mfma_f32_16x16x32_bf16 v[60:63], v[158:161], v[174:177], v[60:63]
	v_mfma_f32_16x16x32_bf16 v[56:59], v[158:161], v[182:185], v[56:59]
	v_mfma_f32_16x16x32_bf16 v[52:55], v[158:161], v[186:189], v[52:55]
	v_mfma_f32_16x16x32_bf16 v[48:51], v[158:161], v[190:193], v[48:51]
	v_mfma_f32_16x16x32_bf16 v[44:47], v[162:165], v[174:177], v[44:47]
	v_mfma_f32_16x16x32_bf16 v[32:35], v[162:165], v[182:185], v[32:35]
	v_mfma_f32_16x16x32_bf16 v[28:31], v[162:165], v[186:189], v[28:31]
	v_mfma_f32_16x16x32_bf16 v[24:27], v[162:165], v[190:193], v[24:27]
	v_mfma_f32_16x16x32_bf16 v[20:23], v[166:169], v[174:177], v[20:23]
	v_mfma_f32_16x16x32_bf16 v[16:19], v[166:169], v[182:185], v[16:19]
	v_mfma_f32_16x16x32_bf16 v[12:15], v[166:169], v[186:189], v[12:15]
	v_mfma_f32_16x16x32_bf16 v[8:11], v[166:169], v[190:193], v[8:11]
	v_mfma_f32_16x16x32_bf16 v[4:7], v[170:173], v[174:177], v[4:7]
	v_mfma_f32_16x16x32_bf16 v[0:3], v[170:173], v[182:185], v[0:3]
	v_mfma_f32_16x16x32_bf16 v[40:43], v[170:173], v[186:189], v[40:43]
	v_mfma_f32_16x16x32_bf16 v[36:39], v[170:173], v[190:193], v[36:39]
	ds_read_b128 v[158:161], v180 offset:8192
	ds_read_b128 v[162:165], v180 offset:10240
	ds_read_b128 v[166:169], v180 offset:12288
	ds_read_b128 v[170:173], v180 offset:14336
	s_waitcnt lgkmcnt(4)
	v_mfma_f32_16x16x32_bf16 v[124:127], v[142:145], v[194:197], v[124:127]
	v_mfma_f32_16x16x32_bf16 v[120:123], v[142:145], v[198:201], v[120:123]
	v_mfma_f32_16x16x32_bf16 v[116:119], v[142:145], v[202:205], v[116:119]
	v_mfma_f32_16x16x32_bf16 v[112:115], v[142:145], v[206:209], v[112:115]
	v_mfma_f32_16x16x32_bf16 v[108:111], v[146:149], v[194:197], v[108:111]
	v_mfma_f32_16x16x32_bf16 v[104:107], v[146:149], v[198:201], v[104:107]
	v_mfma_f32_16x16x32_bf16 v[100:103], v[146:149], v[202:205], v[100:103]
	v_mfma_f32_16x16x32_bf16 v[96:99], v[146:149], v[206:209], v[96:99]
	v_mfma_f32_16x16x32_bf16 v[92:95], v[150:153], v[194:197], v[92:95]
	v_mfma_f32_16x16x32_bf16 v[88:91], v[150:153], v[198:201], v[88:91]
	v_mfma_f32_16x16x32_bf16 v[84:87], v[150:153], v[202:205], v[84:87]
	v_mfma_f32_16x16x32_bf16 v[80:83], v[150:153], v[206:209], v[80:83]
	v_mfma_f32_16x16x32_bf16 v[76:79], v[154:157], v[194:197], v[76:79]
	v_mfma_f32_16x16x32_bf16 v[72:75], v[154:157], v[198:201], v[72:75]
	v_mfma_f32_16x16x32_bf16 v[68:71], v[154:157], v[202:205], v[68:71]
	v_mfma_f32_16x16x32_bf16 v[64:67], v[154:157], v[206:209], v[64:67]
	s_add_u32 s48, s48, 0x80
	s_addc_u32 s49, s49, 0
	s_add_i32 s47, s47, 1
	s_cmp_lt_u32 s47, 31
	s_cbranch_scc0 .Lg7_last
	s_waitcnt lgkmcnt(0)
	s_waitcnt vmcnt(0)
	s_barrier
	s_xor_b32 s61, s61, 0x10000
	s_mov_b32 m0, s61
	s_add_u32 s50, s48, s14
	s_addc_u32 s51, s49, s15
	global_load_lds_dwordx4 v178, s[50:51]
	ds_read_b128 v[142:145], v212
	ds_read_b128 v[146:149], v212 offset:2048
	ds_read_b128 v[150:153], v212 offset:4096
	ds_read_b128 v[154:157], v212 offset:6144
	ds_read_b128 v[174:177], v214 offset:32768
	ds_read_b128 v[182:185], v214 offset:34816
	ds_read_b128 v[186:189], v214 offset:36864
	ds_read_b128 v[190:193], v214 offset:38912
	v_mfma_f32_16x16x32_bf16 v[60:63], v[158:161], v[194:197], v[60:63]
	v_mfma_f32_16x16x32_bf16 v[56:59], v[158:161], v[198:201], v[56:59]
	s_add_u32 m0, s61, 0x2000
	s_add_u32 s50, s48, s16
	s_addc_u32 s51, s49, s17
	global_load_lds_dwordx4 v178, s[50:51]
	v_mfma_f32_16x16x32_bf16 v[52:55], v[158:161], v[202:205], v[52:55]
	v_mfma_f32_16x16x32_bf16 v[48:51], v[158:161], v[206:209], v[48:51]
	s_add_u32 m0, s61, 0x4000
	s_add_u32 s50, s48, s18
	s_addc_u32 s51, s49, s19
	global_load_lds_dwordx4 v178, s[50:51]
	v_mfma_f32_16x16x32_bf16 v[44:47], v[162:165], v[194:197], v[44:47]
	v_mfma_f32_16x16x32_bf16 v[32:35], v[162:165], v[198:201], v[32:35]
	s_add_u32 m0, s61, 0x6000
	s_add_u32 s50, s48, s22
	s_addc_u32 s51, s49, s23
	global_load_lds_dwordx4 v178, s[50:51]
	v_mfma_f32_16x16x32_bf16 v[28:31], v[162:165], v[202:205], v[28:31]
	v_mfma_f32_16x16x32_bf16 v[24:27], v[162:165], v[206:209], v[24:27]
	s_add_u32 m0, s61, 0x8000
	s_add_u32 s50, s48, s36
	s_addc_u32 s51, s49, s37
	global_load_lds_dwordx4 v179, s[50:51]
	v_mfma_f32_16x16x32_bf16 v[20:23], v[166:169], v[194:197], v[20:23]
	v_mfma_f32_16x16x32_bf16 v[16:19], v[166:169], v[198:201], v[16:19]
	s_add_u32 m0, s61, 0xa000
	s_add_u32 s50, s48, s40
	s_addc_u32 s51, s49, s41
	global_load_lds_dwordx4 v179, s[50:51]
	v_mfma_f32_16x16x32_bf16 v[12:15], v[166:169], v[202:205], v[12:15]
	v_mfma_f32_16x16x32_bf16 v[8:11], v[166:169], v[206:209], v[8:11]
	s_add_u32 m0, s61, 0xc000
	s_add_u32 s50, s48, s42
	s_addc_u32 s51, s49, s43
	global_load_lds_dwordx4 v179, s[50:51]
	v_mfma_f32_16x16x32_bf16 v[4:7], v[170:173], v[194:197], v[4:7]
	v_mfma_f32_16x16x32_bf16 v[0:3], v[170:173], v[198:201], v[0:3]
	s_add_u32 m0, s61, 0xe000
	s_add_u32 s50, s48, s44
	s_addc_u32 s51, s49, s45
	global_load_lds_dwordx4 v179, s[50:51]
	v_mfma_f32_16x16x32_bf16 v[40:43], v[170:173], v[202:205], v[40:43]
	v_mfma_f32_16x16x32_bf16 v[36:39], v[170:173], v[206:209], v[36:39]
	ds_read_b128 v[158:161], v212 offset:8192
	ds_read_b128 v[162:165], v212 offset:10240
	ds_read_b128 v[166:169], v212 offset:12288
	ds_read_b128 v[170:173], v212 offset:14336
	s_waitcnt lgkmcnt(4)
	v_mfma_f32_16x16x32_bf16 v[124:127], v[142:145], v[174:177], v[124:127]
	v_mfma_f32_16x16x32_bf16 v[120:123], v[142:145], v[182:185], v[120:123]
	v_mfma_f32_16x16x32_bf16 v[116:119], v[142:145], v[186:189], v[116:119]
	v_mfma_f32_16x16x32_bf16 v[112:115], v[142:145], v[190:193], v[112:115]
	v_mfma_f32_16x16x32_bf16 v[108:111], v[146:149], v[174:177], v[108:111]
	v_mfma_f32_16x16x32_bf16 v[104:107], v[146:149], v[182:185], v[104:107]
	v_mfma_f32_16x16x32_bf16 v[100:103], v[146:149], v[186:189], v[100:103]
	v_mfma_f32_16x16x32_bf16 v[96:99], v[146:149], v[190:193], v[96:99]
	v_mfma_f32_16x16x32_bf16 v[92:95], v[150:153], v[174:177], v[92:95]
	v_mfma_f32_16x16x32_bf16 v[88:91], v[150:153], v[182:185], v[88:91]
	v_mfma_f32_16x16x32_bf16 v[84:87], v[150:153], v[186:189], v[84:87]
	v_mfma_f32_16x16x32_bf16 v[80:83], v[150:153], v[190:193], v[80:83]
	v_mfma_f32_16x16x32_bf16 v[76:79], v[154:157], v[174:177], v[76:79]
	v_mfma_f32_16x16x32_bf16 v[72:75], v[154:157], v[182:185], v[72:75]
	v_mfma_f32_16x16x32_bf16 v[68:71], v[154:157], v[186:189], v[68:71]
	v_mfma_f32_16x16x32_bf16 v[64:67], v[154:157], v[190:193], v[64:67]
	ds_read_b128 v[142:145], v213
	ds_read_b128 v[146:149], v213 offset:2048
	ds_read_b128 v[150:153], v213 offset:4096
	ds_read_b128 v[154:157], v213 offset:6144
	ds_read_b128 v[194:197], v215 offset:32768
	ds_read_b128 v[198:201], v215 offset:34816
	ds_read_b128 v[202:205], v215 offset:36864
	ds_read_b128 v[206:209], v215 offset:38912
	s_waitcnt lgkmcnt(8)
	v_mfma_f32_16x16x32_bf16 v[60:63], v[158:161], v[174:177], v[60:63]
	v_mfma_f32_16x16x32_bf16 v[56:59], v[158:161], v[182:185], v[56:59]
	v_mfma_f32_16x16x32_bf16 v[52:55], v[158:161], v[186:189], v[52:55]
	v_mfma_f32_16x16x32_bf16 v[48:51], v[158:161], v[190:193], v[48:51]
	v_mfma_f32_16x16x32_bf16 v[44:47], v[162:165], v[174:177], v[44:47]
	v_mfma_f32_16x16x32_bf16 v[32:35], v[162:165], v[182:185], v[32:35]
	v_mfma_f32_16x16x32_bf16 v[28:31], v[162:165], v[186:189], v[28:31]
	v_mfma_f32_16x16x32_bf16 v[24:27], v[162:165], v[190:193], v[24:27]
	v_mfma_f32_16x16x32_bf16 v[20:23], v[166:169], v[174:177], v[20:23]
	v_mfma_f32_16x16x32_bf16 v[16:19], v[166:169], v[182:185], v[16:19]
	v_mfma_f32_16x16x32_bf16 v[12:15], v[166:169], v[186:189], v[12:15]
	v_mfma_f32_16x16x32_bf16 v[8:11], v[166:169], v[190:193], v[8:11]
	v_mfma_f32_16x16x32_bf16 v[4:7], v[170:173], v[174:177], v[4:7]
	v_mfma_f32_16x16x32_bf16 v[0:3], v[170:173], v[182:185], v[0:3]
	v_mfma_f32_16x16x32_bf16 v[40:43], v[170:173], v[186:189], v[40:43]
	v_mfma_f32_16x16x32_bf16 v[36:39], v[170:173], v[190:193], v[36:39]
	ds_read_b128 v[158:161], v213 offset:8192
	ds_read_b128 v[162:165], v213 offset:10240
	ds_read_b128 v[166:169], v213 offset:12288
	ds_read_b128 v[170:173], v213 offset:14336
	s_waitcnt lgkmcnt(4)
	v_mfma_f32_16x16x32_bf16 v[124:127], v[142:145], v[194:197], v[124:127]
	v_mfma_f32_16x16x32_bf16 v[120:123], v[142:145], v[198:201], v[120:123]
	v_mfma_f32_16x16x32_bf16 v[116:119], v[142:145], v[202:205], v[116:119]
	v_mfma_f32_16x16x32_bf16 v[112:115], v[142:145], v[206:209], v[112:115]
	v_mfma_f32_16x16x32_bf16 v[108:111], v[146:149], v[194:197], v[108:111]
	v_mfma_f32_16x16x32_bf16 v[104:107], v[146:149], v[198:201], v[104:107]
	v_mfma_f32_16x16x32_bf16 v[100:103], v[146:149], v[202:205], v[100:103]
	v_mfma_f32_16x16x32_bf16 v[96:99], v[146:149], v[206:209], v[96:99]
	v_mfma_f32_16x16x32_bf16 v[92:95], v[150:153], v[194:197], v[92:95]
	v_mfma_f32_16x16x32_bf16 v[88:91], v[150:153], v[198:201], v[88:91]
	v_mfma_f32_16x16x32_bf16 v[84:87], v[150:153], v[202:205], v[84:87]
	v_mfma_f32_16x16x32_bf16 v[80:83], v[150:153], v[206:209], v[80:83]
	v_mfma_f32_16x16x32_bf16 v[76:79], v[154:157], v[194:197], v[76:79]
	v_mfma_f32_16x16x32_bf16 v[72:75], v[154:157], v[198:201], v[72:75]
	v_mfma_f32_16x16x32_bf16 v[68:71], v[154:157], v[202:205], v[68:71]
	v_mfma_f32_16x16x32_bf16 v[64:67], v[154:157], v[206:209], v[64:67]
	s_add_u32 s48, s48, 0x80
	s_addc_u32 s49, s49, 0
	s_add_i32 s47, s47, 1
	s_branch .Lg7_top

.Lg8_top:
	s_waitcnt lgkmcnt(0)
	s_waitcnt vmcnt(0)
	s_barrier
	s_xor_b32 s59, s59, 0x10000
	s_mov_b32 m0, s59
	s_add_u32 s62, s60, s22
	s_addc_u32 s63, s61, s23
	global_load_lds_dwordx4 v178, s[62:63]
	ds_read_b128 v[154:157], v180
	ds_read_b128 v[158:161], v180 offset:2048
	ds_read_b128 v[162:165], v180 offset:4096
	ds_read_b128 v[166:169], v180 offset:6144
	ds_read_b128 v[190:193], v223 offset:32768
	ds_read_b128 v[194:197], v223 offset:34816
	ds_read_b128 v[198:201], v223 offset:36864
	ds_read_b128 v[202:205], v223 offset:38912
	v_mfma_f32_16x16x32_bf16 v[60:63], v[170:173], v[206:209], v[60:63]
	v_mfma_f32_16x16x32_bf16 v[56:59], v[170:173], v[210:213], v[56:59]
	s_add_u32 m0, s59, 0x2000
	s_add_u32 s62, s60, s36
	s_addc_u32 s63, s61, s37
	global_load_lds_dwordx4 v178, s[62:63]
	v_mfma_f32_16x16x32_bf16 v[52:55], v[170:173], v[214:217], v[52:55]
	v_mfma_f32_16x16x32_bf16 v[44:47], v[170:173], v[218:221], v[44:47]
	s_add_u32 m0, s59, 0x4000
	s_add_u32 s62, s60, s38
	s_addc_u32 s63, s61, s39
	global_load_lds_dwordx4 v178, s[62:63]
	v_mfma_f32_16x16x32_bf16 v[36:39], v[174:177], v[206:209], v[36:39]
	v_mfma_f32_16x16x32_bf16 v[32:35], v[174:177], v[210:213], v[32:35]
	s_add_u32 m0, s59, 0x6000
	s_add_u32 s62, s60, s40
	s_addc_u32 s63, s61, s41
	global_load_lds_dwordx4 v178, s[62:63]
	v_mfma_f32_16x16x32_bf16 v[28:31], v[174:177], v[214:217], v[28:31]
	v_mfma_f32_16x16x32_bf16 v[24:27], v[174:177], v[218:221], v[24:27]
	s_add_u32 m0, s59, 0x8000
	s_add_u32 s62, s60, s42
	s_addc_u32 s63, s61, s43
	global_load_lds_dwordx4 v179, s[62:63]
	v_mfma_f32_16x16x32_bf16 v[20:23], v[182:185], v[206:209], v[20:23]
	v_mfma_f32_16x16x32_bf16 v[16:19], v[182:185], v[210:213], v[16:19]
	s_add_u32 m0, s59, 0xa000
	s_add_u32 s62, s60, s44
	s_addc_u32 s63, s61, s45
	global_load_lds_dwordx4 v179, s[62:63]
	v_mfma_f32_16x16x32_bf16 v[12:15], v[182:185], v[214:217], v[12:15]
	v_mfma_f32_16x16x32_bf16 v[8:11], v[182:185], v[218:221], v[8:11]
	s_add_u32 m0, s59, 0xc000
	s_add_u32 s62, s60, s46
	s_addc_u32 s63, s61, s47
	global_load_lds_dwordx4 v179, s[62:63]
	v_mfma_f32_16x16x32_bf16 v[4:7], v[186:189], v[206:209], v[4:7]
	v_mfma_f32_16x16x32_bf16 v[0:3], v[186:189], v[210:213], v[0:3]
	s_add_u32 m0, s59, 0xe000
	s_add_u32 s62, s60, s48
	s_addc_u32 s63, s61, s49
	global_load_lds_dwordx4 v179, s[62:63]
	v_mfma_f32_16x16x32_bf16 v[48:51], v[186:189], v[214:217], v[48:51]
	v_mfma_f32_16x16x32_bf16 v[40:43], v[186:189], v[218:221], v[40:43]
.Lg8_entry:
	ds_read_b128 v[170:173], v180 offset:8192
	ds_read_b128 v[174:177], v180 offset:10240
	ds_read_b128 v[182:185], v180 offset:12288
	ds_read_b128 v[186:189], v180 offset:14336
	s_waitcnt lgkmcnt(4)
	v_mfma_f32_16x16x32_bf16 v[124:127], v[154:157], v[190:193], v[124:127]
	v_mfma_f32_16x16x32_bf16 v[120:123], v[154:157], v[194:197], v[120:123]
	v_mfma_f32_16x16x32_bf16 v[116:119], v[154:157], v[198:201], v[116:119]
	v_mfma_f32_16x16x32_bf16 v[112:115], v[154:157], v[202:205], v[112:115]
	v_mfma_f32_16x16x32_bf16 v[108:111], v[158:161], v[190:193], v[108:111]
	v_mfma_f32_16x16x32_bf16 v[104:107], v[158:161], v[194:197], v[104:107]
	v_mfma_f32_16x16x32_bf16 v[100:103], v[158:161], v[198:201], v[100:103]
	v_mfma_f32_16x16x32_bf16 v[96:99], v[158:161], v[202:205], v[96:99]
	v_mfma_f32_16x16x32_bf16 v[92:95], v[162:165], v[190:193], v[92:95]
	v_mfma_f32_16x16x32_bf16 v[88:91], v[162:165], v[194:197], v[88:91]
	v_mfma_f32_16x16x32_bf16 v[84:87], v[162:165], v[198:201], v[84:87]
	v_mfma_f32_16x16x32_bf16 v[80:83], v[162:165], v[202:205], v[80:83]
	v_mfma_f32_16x16x32_bf16 v[76:79], v[166:169], v[190:193], v[76:79]
	v_mfma_f32_16x16x32_bf16 v[72:75], v[166:169], v[194:197], v[72:75]
	v_mfma_f32_16x16x32_bf16 v[68:71], v[166:169], v[198:201], v[68:71]
	v_mfma_f32_16x16x32_bf16 v[64:67], v[166:169], v[202:205], v[64:67]
	ds_read_b128 v[154:157], v222
	ds_read_b128 v[158:161], v222 offset:2048
	ds_read_b128 v[162:165], v222 offset:4096
	ds_read_b128 v[166:169], v222 offset:6144
	ds_read_b128 v[206:209], v224 offset:32768
	ds_read_b128 v[210:213], v224 offset:34816
	ds_read_b128 v[214:217], v224 offset:36864
	ds_read_b128 v[218:221], v224 offset:38912
	s_waitcnt lgkmcnt(8)
	v_mfma_f32_16x16x32_bf16 v[60:63], v[170:173], v[190:193], v[60:63]
	v_mfma_f32_16x16x32_bf16 v[56:59], v[170:173], v[194:197], v[56:59]
	v_mfma_f32_16x16x32_bf16 v[52:55], v[170:173], v[198:201], v[52:55]
	v_mfma_f32_16x16x32_bf16 v[44:47], v[170:173], v[202:205], v[44:47]
	v_mfma_f32_16x16x32_bf16 v[36:39], v[174:177], v[190:193], v[36:39]
	v_mfma_f32_16x16x32_bf16 v[32:35], v[174:177], v[194:197], v[32:35]
	v_mfma_f32_16x16x32_bf16 v[28:31], v[174:177], v[198:201], v[28:31]
	v_mfma_f32_16x16x32_bf16 v[24:27], v[174:177], v[202:205], v[24:27]
	v_mfma_f32_16x16x32_bf16 v[20:23], v[182:185], v[190:193], v[20:23]
	v_mfma_f32_16x16x32_bf16 v[16:19], v[182:185], v[194:197], v[16:19]
	v_mfma_f32_16x16x32_bf16 v[12:15], v[182:185], v[198:201], v[12:15]
	v_mfma_f32_16x16x32_bf16 v[8:11], v[182:185], v[202:205], v[8:11]
	v_mfma_f32_16x16x32_bf16 v[4:7], v[186:189], v[190:193], v[4:7]
	v_mfma_f32_16x16x32_bf16 v[0:3], v[186:189], v[194:197], v[0:3]
	v_mfma_f32_16x16x32_bf16 v[48:51], v[186:189], v[198:201], v[48:51]
	v_mfma_f32_16x16x32_bf16 v[40:43], v[186:189], v[202:205], v[40:43]
	ds_read_b128 v[170:173], v222 offset:8192
	ds_read_b128 v[174:177], v222 offset:10240
	ds_read_b128 v[182:185], v222 offset:12288
	ds_read_b128 v[186:189], v222 offset:14336
	s_waitcnt lgkmcnt(4)
	v_mfma_f32_16x16x32_bf16 v[124:127], v[154:157], v[206:209], v[124:127]
	v_mfma_f32_16x16x32_bf16 v[120:123], v[154:157], v[210:213], v[120:123]
	v_mfma_f32_16x16x32_bf16 v[116:119], v[154:157], v[214:217], v[116:119]
	v_mfma_f32_16x16x32_bf16 v[112:115], v[154:157], v[218:221], v[112:115]
	v_mfma_f32_16x16x32_bf16 v[108:111], v[158:161], v[206:209], v[108:111]
	v_mfma_f32_16x16x32_bf16 v[104:107], v[158:161], v[210:213], v[104:107]
	v_mfma_f32_16x16x32_bf16 v[100:103], v[158:161], v[214:217], v[100:103]
	v_mfma_f32_16x16x32_bf16 v[96:99], v[158:161], v[218:221], v[96:99]
	v_mfma_f32_16x16x32_bf16 v[92:95], v[162:165], v[206:209], v[92:95]
	v_mfma_f32_16x16x32_bf16 v[88:91], v[162:165], v[210:213], v[88:91]
	v_mfma_f32_16x16x32_bf16 v[84:87], v[162:165], v[214:217], v[84:87]
	v_mfma_f32_16x16x32_bf16 v[80:83], v[162:165], v[218:221], v[80:83]
	v_mfma_f32_16x16x32_bf16 v[76:79], v[166:169], v[206:209], v[76:79]
	v_mfma_f32_16x16x32_bf16 v[72:75], v[166:169], v[210:213], v[72:75]
	v_mfma_f32_16x16x32_bf16 v[68:71], v[166:169], v[214:217], v[68:71]
	v_mfma_f32_16x16x32_bf16 v[64:67], v[166:169], v[218:221], v[64:67]
	s_add_u32 s60, s60, 0x80
	s_addc_u32 s61, s61, 0
	s_add_i32 s57, s57, 1
	s_cmp_lt_u32 s57, 15
	s_cbranch_scc0 .Lg8_last
	s_waitcnt lgkmcnt(0)
	s_waitcnt vmcnt(0)
	s_barrier
	s_xor_b32 s59, s59, 0x10000
	s_mov_b32 m0, s59
	s_add_u32 s62, s60, s22
	s_addc_u32 s63, s61, s23
	global_load_lds_dwordx4 v178, s[62:63]
	ds_read_b128 v[154:157], v225
	ds_read_b128 v[158:161], v225 offset:2048
	ds_read_b128 v[162:165], v225 offset:4096
	ds_read_b128 v[166:169], v225 offset:6144
	ds_read_b128 v[190:193], v227 offset:32768
	ds_read_b128 v[194:197], v227 offset:34816
	ds_read_b128 v[198:201], v227 offset:36864
	ds_read_b128 v[202:205], v227 offset:38912
	v_mfma_f32_16x16x32_bf16 v[60:63], v[170:173], v[206:209], v[60:63]
	v_mfma_f32_16x16x32_bf16 v[56:59], v[170:173], v[210:213], v[56:59]
	s_add_u32 m0, s59, 0x2000
	s_add_u32 s62, s60, s36
	s_addc_u32 s63, s61, s37
	global_load_lds_dwordx4 v178, s[62:63]
	v_mfma_f32_16x16x32_bf16 v[52:55], v[170:173], v[214:217], v[52:55]
	v_mfma_f32_16x16x32_bf16 v[44:47], v[170:173], v[218:221], v[44:47]
	s_add_u32 m0, s59, 0x4000
	s_add_u32 s62, s60, s38
	s_addc_u32 s63, s61, s39
	global_load_lds_dwordx4 v178, s[62:63]
	v_mfma_f32_16x16x32_bf16 v[36:39], v[174:177], v[206:209], v[36:39]
	v_mfma_f32_16x16x32_bf16 v[32:35], v[174:177], v[210:213], v[32:35]
	s_add_u32 m0, s59, 0x6000
	s_add_u32 s62, s60, s40
	s_addc_u32 s63, s61, s41
	global_load_lds_dwordx4 v178, s[62:63]
	v_mfma_f32_16x16x32_bf16 v[28:31], v[174:177], v[214:217], v[28:31]
	v_mfma_f32_16x16x32_bf16 v[24:27], v[174:177], v[218:221], v[24:27]
	s_add_u32 m0, s59, 0x8000
	s_add_u32 s62, s60, s42
	s_addc_u32 s63, s61, s43
	global_load_lds_dwordx4 v179, s[62:63]
	v_mfma_f32_16x16x32_bf16 v[20:23], v[182:185], v[206:209], v[20:23]
	v_mfma_f32_16x16x32_bf16 v[16:19], v[182:185], v[210:213], v[16:19]
	s_add_u32 m0, s59, 0xa000
	s_add_u32 s62, s60, s44
	s_addc_u32 s63, s61, s45
	global_load_lds_dwordx4 v179, s[62:63]
	v_mfma_f32_16x16x32_bf16 v[12:15], v[182:185], v[214:217], v[12:15]
	v_mfma_f32_16x16x32_bf16 v[8:11], v[182:185], v[218:221], v[8:11]
	s_add_u32 m0, s59, 0xc000
	s_add_u32 s62, s60, s46
	s_addc_u32 s63, s61, s47
	global_load_lds_dwordx4 v179, s[62:63]
	v_mfma_f32_16x16x32_bf16 v[4:7], v[186:189], v[206:209], v[4:7]
	v_mfma_f32_16x16x32_bf16 v[0:3], v[186:189], v[210:213], v[0:3]
	s_add_u32 m0, s59, 0xe000
	s_add_u32 s62, s60, s48
	s_addc_u32 s63, s61, s49
	global_load_lds_dwordx4 v179, s[62:63]
	v_mfma_f32_16x16x32_bf16 v[48:51], v[186:189], v[214:217], v[48:51]
	v_mfma_f32_16x16x32_bf16 v[40:43], v[186:189], v[218:221], v[40:43]
	ds_read_b128 v[170:173], v225 offset:8192
	ds_read_b128 v[174:177], v225 offset:10240
	ds_read_b128 v[182:185], v225 offset:12288
	ds_read_b128 v[186:189], v225 offset:14336
	s_waitcnt lgkmcnt(4)
	v_mfma_f32_16x16x32_bf16 v[124:127], v[154:157], v[190:193], v[124:127]
	v_mfma_f32_16x16x32_bf16 v[120:123], v[154:157], v[194:197], v[120:123]
	v_mfma_f32_16x16x32_bf16 v[116:119], v[154:157], v[198:201], v[116:119]
	v_mfma_f32_16x16x32_bf16 v[112:115], v[154:157], v[202:205], v[112:115]
	v_mfma_f32_16x16x32_bf16 v[108:111], v[158:161], v[190:193], v[108:111]
	v_mfma_f32_16x16x32_bf16 v[104:107], v[158:161], v[194:197], v[104:107]
	v_mfma_f32_16x16x32_bf16 v[100:103], v[158:161], v[198:201], v[100:103]
	v_mfma_f32_16x16x32_bf16 v[96:99], v[158:161], v[202:205], v[96:99]
	v_mfma_f32_16x16x32_bf16 v[92:95], v[162:165], v[190:193], v[92:95]
	v_mfma_f32_16x16x32_bf16 v[88:91], v[162:165], v[194:197], v[88:91]
	v_mfma_f32_16x16x32_bf16 v[84:87], v[162:165], v[198:201], v[84:87]
	v_mfma_f32_16x16x32_bf16 v[80:83], v[162:165], v[202:205], v[80:83]
	v_mfma_f32_16x16x32_bf16 v[76:79], v[166:169], v[190:193], v[76:79]
	v_mfma_f32_16x16x32_bf16 v[72:75], v[166:169], v[194:197], v[72:75]
	v_mfma_f32_16x16x32_bf16 v[68:71], v[166:169], v[198:201], v[68:71]
	v_mfma_f32_16x16x32_bf16 v[64:67], v[166:169], v[202:205], v[64:67]
	ds_read_b128 v[154:157], v226
	ds_read_b128 v[158:161], v226 offset:2048
	ds_read_b128 v[162:165], v226 offset:4096
	ds_read_b128 v[166:169], v226 offset:6144
	ds_read_b128 v[206:209], v228 offset:32768
	ds_read_b128 v[210:213], v228 offset:34816
	ds_read_b128 v[214:217], v228 offset:36864
	ds_read_b128 v[218:221], v228 offset:38912
	s_waitcnt lgkmcnt(8)
	v_mfma_f32_16x16x32_bf16 v[60:63], v[170:173], v[190:193], v[60:63]
	v_mfma_f32_16x16x32_bf16 v[56:59], v[170:173], v[194:197], v[56:59]
	v_mfma_f32_16x16x32_bf16 v[52:55], v[170:173], v[198:201], v[52:55]
	v_mfma_f32_16x16x32_bf16 v[44:47], v[170:173], v[202:205], v[44:47]
	v_mfma_f32_16x16x32_bf16 v[36:39], v[174:177], v[190:193], v[36:39]
	v_mfma_f32_16x16x32_bf16 v[32:35], v[174:177], v[194:197], v[32:35]
	v_mfma_f32_16x16x32_bf16 v[28:31], v[174:177], v[198:201], v[28:31]
	v_mfma_f32_16x16x32_bf16 v[24:27], v[174:177], v[202:205], v[24:27]
	v_mfma_f32_16x16x32_bf16 v[20:23], v[182:185], v[190:193], v[20:23]
	v_mfma_f32_16x16x32_bf16 v[16:19], v[182:185], v[194:197], v[16:19]
	v_mfma_f32_16x16x32_bf16 v[12:15], v[182:185], v[198:201], v[12:15]
	v_mfma_f32_16x16x32_bf16 v[8:11], v[182:185], v[202:205], v[8:11]
	v_mfma_f32_16x16x32_bf16 v[4:7], v[186:189], v[190:193], v[4:7]
	v_mfma_f32_16x16x32_bf16 v[0:3], v[186:189], v[194:197], v[0:3]
	v_mfma_f32_16x16x32_bf16 v[48:51], v[186:189], v[198:201], v[48:51]
	v_mfma_f32_16x16x32_bf16 v[40:43], v[186:189], v[202:205], v[40:43]
	ds_read_b128 v[170:173], v226 offset:8192
	ds_read_b128 v[174:177], v226 offset:10240
	ds_read_b128 v[182:185], v226 offset:12288
	ds_read_b128 v[186:189], v226 offset:14336
	s_waitcnt lgkmcnt(4)
	v_mfma_f32_16x16x32_bf16 v[124:127], v[154:157], v[206:209], v[124:127]
	v_mfma_f32_16x16x32_bf16 v[120:123], v[154:157], v[210:213], v[120:123]
	v_mfma_f32_16x16x32_bf16 v[116:119], v[154:157], v[214:217], v[116:119]
	v_mfma_f32_16x16x32_bf16 v[112:115], v[154:157], v[218:221], v[112:115]
	v_mfma_f32_16x16x32_bf16 v[108:111], v[158:161], v[206:209], v[108:111]
	v_mfma_f32_16x16x32_bf16 v[104:107], v[158:161], v[210:213], v[104:107]
	v_mfma_f32_16x16x32_bf16 v[100:103], v[158:161], v[214:217], v[100:103]
	v_mfma_f32_16x16x32_bf16 v[96:99], v[158:161], v[218:221], v[96:99]
	v_mfma_f32_16x16x32_bf16 v[92:95], v[162:165], v[206:209], v[92:95]
	v_mfma_f32_16x16x32_bf16 v[88:91], v[162:165], v[210:213], v[88:91]
	v_mfma_f32_16x16x32_bf16 v[84:87], v[162:165], v[214:217], v[84:87]
	v_mfma_f32_16x16x32_bf16 v[80:83], v[162:165], v[218:221], v[80:83]
	v_mfma_f32_16x16x32_bf16 v[76:79], v[166:169], v[206:209], v[76:79]
	v_mfma_f32_16x16x32_bf16 v[72:75], v[166:169], v[210:213], v[72:75]
	v_mfma_f32_16x16x32_bf16 v[68:71], v[166:169], v[214:217], v[68:71]
	v_mfma_f32_16x16x32_bf16 v[64:67], v[166:169], v[218:221], v[64:67]
	s_add_u32 s60, s60, 0x80
	s_addc_u32 s61, s61, 0
	s_add_i32 s57, s57, 1
	s_branch .Lg8_top

.Lg9_top:
	s_waitcnt lgkmcnt(0)
	s_waitcnt vmcnt(0)
	s_barrier
	s_xor_b32 s59, s59, 0x10000
	s_mov_b32 m0, s59
	s_add_u32 s46, s44, s12
	s_addc_u32 s47, s45, s13
	global_load_lds_dwordx4 v178, s[46:47]
	ds_read_b128 v[142:145], v141
	ds_read_b128 v[146:149], v141 offset:2048
	ds_read_b128 v[150:153], v141 offset:4096
	ds_read_b128 v[154:157], v141 offset:6144
	ds_read_b128 v[174:177], v210 offset:32768
	ds_read_b128 v[182:185], v210 offset:34816
	ds_read_b128 v[186:189], v210 offset:36864
	ds_read_b128 v[190:193], v210 offset:38912
	v_mfma_f32_16x16x32_bf16 v[60:63], v[158:161], v[194:197], v[60:63]
	v_mfma_f32_16x16x32_bf16 v[56:59], v[158:161], v[198:201], v[56:59]
	s_add_u32 m0, s59, 0x2000
	s_add_u32 s46, s44, s14
	s_addc_u32 s47, s45, s15
	global_load_lds_dwordx4 v178, s[46:47]
	v_mfma_f32_16x16x32_bf16 v[52:55], v[158:161], v[202:205], v[52:55]
	v_mfma_f32_16x16x32_bf16 v[48:51], v[158:161], v[206:209], v[48:51]
	s_add_u32 m0, s59, 0x4000
	s_add_u32 s46, s44, s16
	s_addc_u32 s47, s45, s17
	global_load_lds_dwordx4 v178, s[46:47]
	v_mfma_f32_16x16x32_bf16 v[44:47], v[162:165], v[194:197], v[44:47]
	v_mfma_f32_16x16x32_bf16 v[32:35], v[162:165], v[198:201], v[32:35]
	s_add_u32 m0, s59, 0x6000
	s_add_u32 s46, s44, s18
	s_addc_u32 s47, s45, s19
	global_load_lds_dwordx4 v178, s[46:47]
	v_mfma_f32_16x16x32_bf16 v[28:31], v[162:165], v[202:205], v[28:31]
	v_mfma_f32_16x16x32_bf16 v[24:27], v[162:165], v[206:209], v[24:27]
	s_add_u32 m0, s59, 0x8000
	s_add_u32 s46, s44, s22
	s_addc_u32 s47, s45, s23
	global_load_lds_dwordx4 v179, s[46:47]
	v_mfma_f32_16x16x32_bf16 v[20:23], v[166:169], v[194:197], v[20:23]
	v_mfma_f32_16x16x32_bf16 v[16:19], v[166:169], v[198:201], v[16:19]
	s_add_u32 m0, s59, 0xa000
	s_add_u32 s46, s44, s36
	s_addc_u32 s47, s45, s37
	global_load_lds_dwordx4 v179, s[46:47]
	v_mfma_f32_16x16x32_bf16 v[12:15], v[166:169], v[202:205], v[12:15]
	v_mfma_f32_16x16x32_bf16 v[8:11], v[166:169], v[206:209], v[8:11]
	s_add_u32 m0, s59, 0xc000
	s_add_u32 s46, s44, s38
	s_addc_u32 s47, s45, s39
	global_load_lds_dwordx4 v179, s[46:47]
	v_mfma_f32_16x16x32_bf16 v[4:7], v[170:173], v[194:197], v[4:7]
	v_mfma_f32_16x16x32_bf16 v[0:3], v[170:173], v[198:201], v[0:3]
	s_add_u32 m0, s59, 0xe000
	s_add_u32 s46, s44, s40
	s_addc_u32 s47, s45, s41
	global_load_lds_dwordx4 v179, s[46:47]
	v_mfma_f32_16x16x32_bf16 v[40:43], v[170:173], v[202:205], v[40:43]
	v_mfma_f32_16x16x32_bf16 v[36:39], v[170:173], v[206:209], v[36:39]
.Lg9_entry:
	ds_read_b128 v[158:161], v141 offset:8192
	ds_read_b128 v[162:165], v141 offset:10240
	ds_read_b128 v[166:169], v141 offset:12288
	ds_read_b128 v[170:173], v141 offset:14336
	s_waitcnt lgkmcnt(4)
	v_mfma_f32_16x16x32_bf16 v[124:127], v[142:145], v[174:177], v[124:127]
	v_mfma_f32_16x16x32_bf16 v[120:123], v[142:145], v[182:185], v[120:123]
	v_mfma_f32_16x16x32_bf16 v[116:119], v[142:145], v[186:189], v[116:119]
	v_mfma_f32_16x16x32_bf16 v[112:115], v[142:145], v[190:193], v[112:115]
	v_mfma_f32_16x16x32_bf16 v[108:111], v[146:149], v[174:177], v[108:111]
	v_mfma_f32_16x16x32_bf16 v[104:107], v[146:149], v[182:185], v[104:107]
	v_mfma_f32_16x16x32_bf16 v[100:103], v[146:149], v[186:189], v[100:103]
	v_mfma_f32_16x16x32_bf16 v[96:99], v[146:149], v[190:193], v[96:99]
	v_mfma_f32_16x16x32_bf16 v[92:95], v[150:153], v[174:177], v[92:95]
	v_mfma_f32_16x16x32_bf16 v[88:91], v[150:153], v[182:185], v[88:91]
	v_mfma_f32_16x16x32_bf16 v[84:87], v[150:153], v[186:189], v[84:87]
	v_mfma_f32_16x16x32_bf16 v[80:83], v[150:153], v[190:193], v[80:83]
	v_mfma_f32_16x16x32_bf16 v[76:79], v[154:157], v[174:177], v[76:79]
	v_mfma_f32_16x16x32_bf16 v[72:75], v[154:157], v[182:185], v[72:75]
	v_mfma_f32_16x16x32_bf16 v[68:71], v[154:157], v[186:189], v[68:71]
	v_mfma_f32_16x16x32_bf16 v[64:67], v[154:157], v[190:193], v[64:67]
	ds_read_b128 v[142:145], v180
	ds_read_b128 v[146:149], v180 offset:2048
	ds_read_b128 v[150:153], v180 offset:4096
	ds_read_b128 v[154:157], v180 offset:6144
	ds_read_b128 v[194:197], v211 offset:32768
	ds_read_b128 v[198:201], v211 offset:34816
	ds_read_b128 v[202:205], v211 offset:36864
	ds_read_b128 v[206:209], v211 offset:38912
	s_waitcnt lgkmcnt(8)
	v_mfma_f32_16x16x32_bf16 v[60:63], v[158:161], v[174:177], v[60:63]
	v_mfma_f32_16x16x32_bf16 v[56:59], v[158:161], v[182:185], v[56:59]
	v_mfma_f32_16x16x32_bf16 v[52:55], v[158:161], v[186:189], v[52:55]
	v_mfma_f32_16x16x32_bf16 v[48:51], v[158:161], v[190:193], v[48:51]
	v_mfma_f32_16x16x32_bf16 v[44:47], v[162:165], v[174:177], v[44:47]
	v_mfma_f32_16x16x32_bf16 v[32:35], v[162:165], v[182:185], v[32:35]
	v_mfma_f32_16x16x32_bf16 v[28:31], v[162:165], v[186:189], v[28:31]
	v_mfma_f32_16x16x32_bf16 v[24:27], v[162:165], v[190:193], v[24:27]
	v_mfma_f32_16x16x32_bf16 v[20:23], v[166:169], v[174:177], v[20:23]
	v_mfma_f32_16x16x32_bf16 v[16:19], v[166:169], v[182:185], v[16:19]
	v_mfma_f32_16x16x32_bf16 v[12:15], v[166:169], v[186:189], v[12:15]
	v_mfma_f32_16x16x32_bf16 v[8:11], v[166:169], v[190:193], v[8:11]
	v_mfma_f32_16x16x32_bf16 v[4:7], v[170:173], v[174:177], v[4:7]
	v_mfma_f32_16x16x32_bf16 v[0:3], v[170:173], v[182:185], v[0:3]
	v_mfma_f32_16x16x32_bf16 v[40:43], v[170:173], v[186:189], v[40:43]
	v_mfma_f32_16x16x32_bf16 v[36:39], v[170:173], v[190:193], v[36:39]
	ds_read_b128 v[158:161], v180 offset:8192
	ds_read_b128 v[162:165], v180 offset:10240
	ds_read_b128 v[166:169], v180 offset:12288
	ds_read_b128 v[170:173], v180 offset:14336
	s_waitcnt lgkmcnt(4)
	v_mfma_f32_16x16x32_bf16 v[124:127], v[142:145], v[194:197], v[124:127]
	v_mfma_f32_16x16x32_bf16 v[120:123], v[142:145], v[198:201], v[120:123]
	v_mfma_f32_16x16x32_bf16 v[116:119], v[142:145], v[202:205], v[116:119]
	v_mfma_f32_16x16x32_bf16 v[112:115], v[142:145], v[206:209], v[112:115]
	v_mfma_f32_16x16x32_bf16 v[108:111], v[146:149], v[194:197], v[108:111]
	v_mfma_f32_16x16x32_bf16 v[104:107], v[146:149], v[198:201], v[104:107]
	v_mfma_f32_16x16x32_bf16 v[100:103], v[146:149], v[202:205], v[100:103]
	v_mfma_f32_16x16x32_bf16 v[96:99], v[146:149], v[206:209], v[96:99]
	v_mfma_f32_16x16x32_bf16 v[92:95], v[150:153], v[194:197], v[92:95]
	v_mfma_f32_16x16x32_bf16 v[88:91], v[150:153], v[198:201], v[88:91]
	v_mfma_f32_16x16x32_bf16 v[84:87], v[150:153], v[202:205], v[84:87]
	v_mfma_f32_16x16x32_bf16 v[80:83], v[150:153], v[206:209], v[80:83]
	v_mfma_f32_16x16x32_bf16 v[76:79], v[154:157], v[194:197], v[76:79]
	v_mfma_f32_16x16x32_bf16 v[72:75], v[154:157], v[198:201], v[72:75]
	v_mfma_f32_16x16x32_bf16 v[68:71], v[154:157], v[202:205], v[68:71]
	v_mfma_f32_16x16x32_bf16 v[64:67], v[154:157], v[206:209], v[64:67]
	s_add_u32 s44, s44, 0x80
	s_addc_u32 s45, s45, 0
	s_add_i32 s43, s43, 1
	s_cmp_lt_u32 s43, 31
	s_cbranch_scc0 .Lg9_last
	s_waitcnt lgkmcnt(0)
	s_waitcnt vmcnt(0)
	s_barrier
	s_xor_b32 s59, s59, 0x10000
	s_mov_b32 m0, s59
	s_add_u32 s46, s44, s12
	s_addc_u32 s47, s45, s13
	global_load_lds_dwordx4 v178, s[46:47]
	ds_read_b128 v[142:145], v212
	ds_read_b128 v[146:149], v212 offset:2048
	ds_read_b128 v[150:153], v212 offset:4096
	ds_read_b128 v[154:157], v212 offset:6144
	ds_read_b128 v[174:177], v214 offset:32768
	ds_read_b128 v[182:185], v214 offset:34816
	ds_read_b128 v[186:189], v214 offset:36864
	ds_read_b128 v[190:193], v214 offset:38912
	v_mfma_f32_16x16x32_bf16 v[60:63], v[158:161], v[194:197], v[60:63]
	v_mfma_f32_16x16x32_bf16 v[56:59], v[158:161], v[198:201], v[56:59]
	s_add_u32 m0, s59, 0x2000
	s_add_u32 s46, s44, s14
	s_addc_u32 s47, s45, s15
	global_load_lds_dwordx4 v178, s[46:47]
	v_mfma_f32_16x16x32_bf16 v[52:55], v[158:161], v[202:205], v[52:55]
	v_mfma_f32_16x16x32_bf16 v[48:51], v[158:161], v[206:209], v[48:51]
	s_add_u32 m0, s59, 0x4000
	s_add_u32 s46, s44, s16
	s_addc_u32 s47, s45, s17
	global_load_lds_dwordx4 v178, s[46:47]
	v_mfma_f32_16x16x32_bf16 v[44:47], v[162:165], v[194:197], v[44:47]
	v_mfma_f32_16x16x32_bf16 v[32:35], v[162:165], v[198:201], v[32:35]
	s_add_u32 m0, s59, 0x6000
	s_add_u32 s46, s44, s18
	s_addc_u32 s47, s45, s19
	global_load_lds_dwordx4 v178, s[46:47]
	v_mfma_f32_16x16x32_bf16 v[28:31], v[162:165], v[202:205], v[28:31]
	v_mfma_f32_16x16x32_bf16 v[24:27], v[162:165], v[206:209], v[24:27]
	s_add_u32 m0, s59, 0x8000
	s_add_u32 s46, s44, s22
	s_addc_u32 s47, s45, s23
	global_load_lds_dwordx4 v179, s[46:47]
	v_mfma_f32_16x16x32_bf16 v[20:23], v[166:169], v[194:197], v[20:23]
	v_mfma_f32_16x16x32_bf16 v[16:19], v[166:169], v[198:201], v[16:19]
	s_add_u32 m0, s59, 0xa000
	s_add_u32 s46, s44, s36
	s_addc_u32 s47, s45, s37
	global_load_lds_dwordx4 v179, s[46:47]
	v_mfma_f32_16x16x32_bf16 v[12:15], v[166:169], v[202:205], v[12:15]
	v_mfma_f32_16x16x32_bf16 v[8:11], v[166:169], v[206:209], v[8:11]
	s_add_u32 m0, s59, 0xc000
	s_add_u32 s46, s44, s38
	s_addc_u32 s47, s45, s39
	global_load_lds_dwordx4 v179, s[46:47]
	v_mfma_f32_16x16x32_bf16 v[4:7], v[170:173], v[194:197], v[4:7]
	v_mfma_f32_16x16x32_bf16 v[0:3], v[170:173], v[198:201], v[0:3]
	s_add_u32 m0, s59, 0xe000
	s_add_u32 s46, s44, s40
	s_addc_u32 s47, s45, s41
	global_load_lds_dwordx4 v179, s[46:47]
	v_mfma_f32_16x16x32_bf16 v[40:43], v[170:173], v[202:205], v[40:43]
	v_mfma_f32_16x16x32_bf16 v[36:39], v[170:173], v[206:209], v[36:39]
	ds_read_b128 v[158:161], v212 offset:8192
	ds_read_b128 v[162:165], v212 offset:10240
	ds_read_b128 v[166:169], v212 offset:12288
	ds_read_b128 v[170:173], v212 offset:14336
	s_waitcnt lgkmcnt(4)
	v_mfma_f32_16x16x32_bf16 v[124:127], v[142:145], v[174:177], v[124:127]
	v_mfma_f32_16x16x32_bf16 v[120:123], v[142:145], v[182:185], v[120:123]
	v_mfma_f32_16x16x32_bf16 v[116:119], v[142:145], v[186:189], v[116:119]
	v_mfma_f32_16x16x32_bf16 v[112:115], v[142:145], v[190:193], v[112:115]
	v_mfma_f32_16x16x32_bf16 v[108:111], v[146:149], v[174:177], v[108:111]
	v_mfma_f32_16x16x32_bf16 v[104:107], v[146:149], v[182:185], v[104:107]
	v_mfma_f32_16x16x32_bf16 v[100:103], v[146:149], v[186:189], v[100:103]
	v_mfma_f32_16x16x32_bf16 v[96:99], v[146:149], v[190:193], v[96:99]
	v_mfma_f32_16x16x32_bf16 v[92:95], v[150:153], v[174:177], v[92:95]
	v_mfma_f32_16x16x32_bf16 v[88:91], v[150:153], v[182:185], v[88:91]
	v_mfma_f32_16x16x32_bf16 v[84:87], v[150:153], v[186:189], v[84:87]
	v_mfma_f32_16x16x32_bf16 v[80:83], v[150:153], v[190:193], v[80:83]
	v_mfma_f32_16x16x32_bf16 v[76:79], v[154:157], v[174:177], v[76:79]
	v_mfma_f32_16x16x32_bf16 v[72:75], v[154:157], v[182:185], v[72:75]
	v_mfma_f32_16x16x32_bf16 v[68:71], v[154:157], v[186:189], v[68:71]
	v_mfma_f32_16x16x32_bf16 v[64:67], v[154:157], v[190:193], v[64:67]
	ds_read_b128 v[142:145], v213
	ds_read_b128 v[146:149], v213 offset:2048
	ds_read_b128 v[150:153], v213 offset:4096
	ds_read_b128 v[154:157], v213 offset:6144
	ds_read_b128 v[194:197], v215 offset:32768
	ds_read_b128 v[198:201], v215 offset:34816
	ds_read_b128 v[202:205], v215 offset:36864
	ds_read_b128 v[206:209], v215 offset:38912
	s_waitcnt lgkmcnt(8)
	v_mfma_f32_16x16x32_bf16 v[60:63], v[158:161], v[174:177], v[60:63]
	v_mfma_f32_16x16x32_bf16 v[56:59], v[158:161], v[182:185], v[56:59]
	v_mfma_f32_16x16x32_bf16 v[52:55], v[158:161], v[186:189], v[52:55]
	v_mfma_f32_16x16x32_bf16 v[48:51], v[158:161], v[190:193], v[48:51]
	v_mfma_f32_16x16x32_bf16 v[44:47], v[162:165], v[174:177], v[44:47]
	v_mfma_f32_16x16x32_bf16 v[32:35], v[162:165], v[182:185], v[32:35]
	v_mfma_f32_16x16x32_bf16 v[28:31], v[162:165], v[186:189], v[28:31]
	v_mfma_f32_16x16x32_bf16 v[24:27], v[162:165], v[190:193], v[24:27]
	v_mfma_f32_16x16x32_bf16 v[20:23], v[166:169], v[174:177], v[20:23]
	v_mfma_f32_16x16x32_bf16 v[16:19], v[166:169], v[182:185], v[16:19]
	v_mfma_f32_16x16x32_bf16 v[12:15], v[166:169], v[186:189], v[12:15]
	v_mfma_f32_16x16x32_bf16 v[8:11], v[166:169], v[190:193], v[8:11]
	v_mfma_f32_16x16x32_bf16 v[4:7], v[170:173], v[174:177], v[4:7]
	v_mfma_f32_16x16x32_bf16 v[0:3], v[170:173], v[182:185], v[0:3]
	v_mfma_f32_16x16x32_bf16 v[40:43], v[170:173], v[186:189], v[40:43]
	v_mfma_f32_16x16x32_bf16 v[36:39], v[170:173], v[190:193], v[36:39]
	ds_read_b128 v[158:161], v213 offset:8192
	ds_read_b128 v[162:165], v213 offset:10240
	ds_read_b128 v[166:169], v213 offset:12288
	ds_read_b128 v[170:173], v213 offset:14336
	s_waitcnt lgkmcnt(4)
	v_mfma_f32_16x16x32_bf16 v[124:127], v[142:145], v[194:197], v[124:127]
	v_mfma_f32_16x16x32_bf16 v[120:123], v[142:145], v[198:201], v[120:123]
	v_mfma_f32_16x16x32_bf16 v[116:119], v[142:145], v[202:205], v[116:119]
	v_mfma_f32_16x16x32_bf16 v[112:115], v[142:145], v[206:209], v[112:115]
	v_mfma_f32_16x16x32_bf16 v[108:111], v[146:149], v[194:197], v[108:111]
	v_mfma_f32_16x16x32_bf16 v[104:107], v[146:149], v[198:201], v[104:107]
	v_mfma_f32_16x16x32_bf16 v[100:103], v[146:149], v[202:205], v[100:103]
	v_mfma_f32_16x16x32_bf16 v[96:99], v[146:149], v[206:209], v[96:99]
	v_mfma_f32_16x16x32_bf16 v[92:95], v[150:153], v[194:197], v[92:95]
	v_mfma_f32_16x16x32_bf16 v[88:91], v[150:153], v[198:201], v[88:91]
	v_mfma_f32_16x16x32_bf16 v[84:87], v[150:153], v[202:205], v[84:87]
	v_mfma_f32_16x16x32_bf16 v[80:83], v[150:153], v[206:209], v[80:83]
	v_mfma_f32_16x16x32_bf16 v[76:79], v[154:157], v[194:197], v[76:79]
	v_mfma_f32_16x16x32_bf16 v[72:75], v[154:157], v[198:201], v[72:75]
	v_mfma_f32_16x16x32_bf16 v[68:71], v[154:157], v[202:205], v[68:71]
	v_mfma_f32_16x16x32_bf16 v[64:67], v[154:157], v[206:209], v[64:67]
	s_add_u32 s44, s44, 0x80
	s_addc_u32 s45, s45, 0
	s_add_i32 s43, s43, 1
	s_branch .Lg9_top

.Lg10_top:
	s_waitcnt lgkmcnt(0)
	s_waitcnt vmcnt(0)
	s_barrier
	s_xor_b32 s57, s57, 0x10000
	s_mov_b32 m0, s57
	s_add_u32 s46, s44, s14
	s_addc_u32 s47, s45, s15
	global_load_lds_dwordx4 v144, s[46:47]
	ds_read_b128 v[156:159], v143
	ds_read_b128 v[160:163], v143 offset:2048
	ds_read_b128 v[164:167], v143 offset:4096
	ds_read_b128 v[168:171], v143 offset:6144
	ds_read_b128 v[190:193], v180 offset:32768
	ds_read_b128 v[194:197], v180 offset:34816
	ds_read_b128 v[198:201], v180 offset:36864
	ds_read_b128 v[202:205], v180 offset:38912
	v_mfma_f32_16x16x32_bf16 v[60:63], v[172:175], v[206:209], v[60:63]
	v_mfma_f32_16x16x32_bf16 v[52:55], v[172:175], v[210:213], v[52:55]
	s_add_u32 m0, s57, 0x2000
	s_add_u32 s46, s44, s16
	s_addc_u32 s47, s45, s17
	global_load_lds_dwordx4 v144, s[46:47]
	v_mfma_f32_16x16x32_bf16 v[56:59], v[172:175], v[214:217], v[56:59]
	v_mfma_f32_16x16x32_bf16 v[48:51], v[172:175], v[218:221], v[48:51]
	s_add_u32 m0, s57, 0x4000
	s_add_u32 s46, s44, s18
	s_addc_u32 s47, s45, s19
	global_load_lds_dwordx4 v144, s[46:47]
	v_mfma_f32_16x16x32_bf16 v[44:47], v[176:179], v[206:209], v[44:47]
	v_mfma_f32_16x16x32_bf16 v[36:39], v[176:179], v[210:213], v[36:39]
	s_add_u32 m0, s57, 0x6000
	s_add_u32 s46, s44, s22
	s_addc_u32 s47, s45, s23
	global_load_lds_dwordx4 v144, s[46:47]
	v_mfma_f32_16x16x32_bf16 v[40:43], v[176:179], v[214:217], v[40:43]
	v_mfma_f32_16x16x32_bf16 v[32:35], v[176:179], v[218:221], v[32:35]
	s_add_u32 m0, s57, 0x8000
	s_add_u32 s46, s44, s30
	s_addc_u32 s47, s45, s31
	global_load_lds_dwordx4 v145, s[46:47]
	v_mfma_f32_16x16x32_bf16 v[28:31], v[182:185], v[206:209], v[28:31]
	v_mfma_f32_16x16x32_bf16 v[16:19], v[182:185], v[210:213], v[16:19]
	s_add_u32 m0, s57, 0xa000
	s_add_u32 s46, s44, s36
	s_addc_u32 s47, s45, s37
	global_load_lds_dwordx4 v145, s[46:47]
	v_mfma_f32_16x16x32_bf16 v[24:27], v[182:185], v[214:217], v[24:27]
	v_mfma_f32_16x16x32_bf16 v[12:15], v[182:185], v[218:221], v[12:15]
	s_add_u32 m0, s57, 0xc000
	s_add_u32 s46, s44, s38
	s_addc_u32 s47, s45, s39
	global_load_lds_dwordx4 v145, s[46:47]
	v_mfma_f32_16x16x32_bf16 v[4:7], v[186:189], v[206:209], v[4:7]
	v_mfma_f32_16x16x32_bf16 v[0:3], v[186:189], v[210:213], v[0:3]
	s_add_u32 m0, s57, 0xe000
	s_add_u32 s46, s44, s40
	s_addc_u32 s47, s45, s41
	global_load_lds_dwordx4 v145, s[46:47]
	v_mfma_f32_16x16x32_bf16 v[20:23], v[186:189], v[214:217], v[20:23]
	v_mfma_f32_16x16x32_bf16 v[8:11], v[186:189], v[218:221], v[8:11]
.Lg10_entry:
	ds_read_b128 v[172:175], v143 offset:8192
	ds_read_b128 v[176:179], v143 offset:10240
	ds_read_b128 v[182:185], v143 offset:12288
	ds_read_b128 v[186:189], v143 offset:14336
	s_waitcnt lgkmcnt(4)
	v_mfma_f32_16x16x32_bf16 v[124:127], v[156:159], v[190:193], v[124:127]
	v_mfma_f32_16x16x32_bf16 v[116:119], v[156:159], v[194:197], v[116:119]
	v_mfma_f32_16x16x32_bf16 v[120:123], v[156:159], v[198:201], v[120:123]
	v_mfma_f32_16x16x32_bf16 v[112:115], v[156:159], v[202:205], v[112:115]
	v_mfma_f32_16x16x32_bf16 v[108:111], v[160:163], v[190:193], v[108:111]
	v_mfma_f32_16x16x32_bf16 v[100:103], v[160:163], v[194:197], v[100:103]
	v_mfma_f32_16x16x32_bf16 v[104:107], v[160:163], v[198:201], v[104:107]
	v_mfma_f32_16x16x32_bf16 v[96:99], v[160:163], v[202:205], v[96:99]
	v_mfma_f32_16x16x32_bf16 v[92:95], v[164:167], v[190:193], v[92:95]
	v_mfma_f32_16x16x32_bf16 v[84:87], v[164:167], v[194:197], v[84:87]
	v_mfma_f32_16x16x32_bf16 v[88:91], v[164:167], v[198:201], v[88:91]
	v_mfma_f32_16x16x32_bf16 v[80:83], v[164:167], v[202:205], v[80:83]
	v_mfma_f32_16x16x32_bf16 v[76:79], v[168:171], v[190:193], v[76:79]
	v_mfma_f32_16x16x32_bf16 v[68:71], v[168:171], v[194:197], v[68:71]
	v_mfma_f32_16x16x32_bf16 v[72:75], v[168:171], v[198:201], v[72:75]
	v_mfma_f32_16x16x32_bf16 v[64:67], v[168:171], v[202:205], v[64:67]
	ds_read_b128 v[156:159], v155
	ds_read_b128 v[160:163], v155 offset:2048
	ds_read_b128 v[164:167], v155 offset:4096
	ds_read_b128 v[168:171], v155 offset:6144
	ds_read_b128 v[206:209], v222 offset:32768
	ds_read_b128 v[210:213], v222 offset:34816
	ds_read_b128 v[214:217], v222 offset:36864
	ds_read_b128 v[218:221], v222 offset:38912
	s_waitcnt lgkmcnt(8)
	v_mfma_f32_16x16x32_bf16 v[60:63], v[172:175], v[190:193], v[60:63]
	v_mfma_f32_16x16x32_bf16 v[52:55], v[172:175], v[194:197], v[52:55]
	v_mfma_f32_16x16x32_bf16 v[56:59], v[172:175], v[198:201], v[56:59]
	v_mfma_f32_16x16x32_bf16 v[48:51], v[172:175], v[202:205], v[48:51]
	v_mfma_f32_16x16x32_bf16 v[44:47], v[176:179], v[190:193], v[44:47]
	v_mfma_f32_16x16x32_bf16 v[36:39], v[176:179], v[194:197], v[36:39]
	v_mfma_f32_16x16x32_bf16 v[40:43], v[176:179], v[198:201], v[40:43]
	v_mfma_f32_16x16x32_bf16 v[32:35], v[176:179], v[202:205], v[32:35]
	v_mfma_f32_16x16x32_bf16 v[28:31], v[182:185], v[190:193], v[28:31]
	v_mfma_f32_16x16x32_bf16 v[16:19], v[182:185], v[194:197], v[16:19]
	v_mfma_f32_16x16x32_bf16 v[24:27], v[182:185], v[198:201], v[24:27]
	v_mfma_f32_16x16x32_bf16 v[12:15], v[182:185], v[202:205], v[12:15]
	v_mfma_f32_16x16x32_bf16 v[4:7], v[186:189], v[190:193], v[4:7]
	v_mfma_f32_16x16x32_bf16 v[0:3], v[186:189], v[194:197], v[0:3]
	v_mfma_f32_16x16x32_bf16 v[20:23], v[186:189], v[198:201], v[20:23]
	v_mfma_f32_16x16x32_bf16 v[8:11], v[186:189], v[202:205], v[8:11]
	ds_read_b128 v[172:175], v155 offset:8192
	ds_read_b128 v[176:179], v155 offset:10240
	ds_read_b128 v[182:185], v155 offset:12288
	ds_read_b128 v[186:189], v155 offset:14336
	s_waitcnt lgkmcnt(4)
	v_mfma_f32_16x16x32_bf16 v[124:127], v[156:159], v[206:209], v[124:127]
	v_mfma_f32_16x16x32_bf16 v[116:119], v[156:159], v[210:213], v[116:119]
	v_mfma_f32_16x16x32_bf16 v[120:123], v[156:159], v[214:217], v[120:123]
	v_mfma_f32_16x16x32_bf16 v[112:115], v[156:159], v[218:221], v[112:115]
	v_mfma_f32_16x16x32_bf16 v[108:111], v[160:163], v[206:209], v[108:111]
	v_mfma_f32_16x16x32_bf16 v[100:103], v[160:163], v[210:213], v[100:103]
	v_mfma_f32_16x16x32_bf16 v[104:107], v[160:163], v[214:217], v[104:107]
	v_mfma_f32_16x16x32_bf16 v[96:99], v[160:163], v[218:221], v[96:99]
	v_mfma_f32_16x16x32_bf16 v[92:95], v[164:167], v[206:209], v[92:95]
	v_mfma_f32_16x16x32_bf16 v[84:87], v[164:167], v[210:213], v[84:87]
	v_mfma_f32_16x16x32_bf16 v[88:91], v[164:167], v[214:217], v[88:91]
	v_mfma_f32_16x16x32_bf16 v[80:83], v[164:167], v[218:221], v[80:83]
	v_mfma_f32_16x16x32_bf16 v[76:79], v[168:171], v[206:209], v[76:79]
	v_mfma_f32_16x16x32_bf16 v[68:71], v[168:171], v[210:213], v[68:71]
	v_mfma_f32_16x16x32_bf16 v[72:75], v[168:171], v[214:217], v[72:75]
	v_mfma_f32_16x16x32_bf16 v[64:67], v[168:171], v[218:221], v[64:67]
	s_add_u32 s44, s44, 0x80
	s_addc_u32 s45, s45, 0
	s_add_i32 s43, s43, 1
	s_cmp_lt_u32 s43, 15
	s_cbranch_scc0 .Lg10_last
	s_waitcnt lgkmcnt(0)
	s_waitcnt vmcnt(0)
	s_barrier
	s_xor_b32 s57, s57, 0x10000
	s_mov_b32 m0, s57
	s_add_u32 s46, s44, s14
	s_addc_u32 s47, s45, s15
	global_load_lds_dwordx4 v144, s[46:47]
	ds_read_b128 v[156:159], v223
	ds_read_b128 v[160:163], v223 offset:2048
	ds_read_b128 v[164:167], v223 offset:4096
	ds_read_b128 v[168:171], v223 offset:6144
	ds_read_b128 v[190:193], v225 offset:32768
	ds_read_b128 v[194:197], v225 offset:34816
	ds_read_b128 v[198:201], v225 offset:36864
	ds_read_b128 v[202:205], v225 offset:38912
	v_mfma_f32_16x16x32_bf16 v[60:63], v[172:175], v[206:209], v[60:63]
	v_mfma_f32_16x16x32_bf16 v[52:55], v[172:175], v[210:213], v[52:55]
	s_add_u32 m0, s57, 0x2000
	s_add_u32 s46, s44, s16
	s_addc_u32 s47, s45, s17
	global_load_lds_dwordx4 v144, s[46:47]
	v_mfma_f32_16x16x32_bf16 v[56:59], v[172:175], v[214:217], v[56:59]
	v_mfma_f32_16x16x32_bf16 v[48:51], v[172:175], v[218:221], v[48:51]
	s_add_u32 m0, s57, 0x4000
	s_add_u32 s46, s44, s18
	s_addc_u32 s47, s45, s19
	global_load_lds_dwordx4 v144, s[46:47]
	v_mfma_f32_16x16x32_bf16 v[44:47], v[176:179], v[206:209], v[44:47]
	v_mfma_f32_16x16x32_bf16 v[36:39], v[176:179], v[210:213], v[36:39]
	s_add_u32 m0, s57, 0x6000
	s_add_u32 s46, s44, s22
	s_addc_u32 s47, s45, s23
	global_load_lds_dwordx4 v144, s[46:47]
	v_mfma_f32_16x16x32_bf16 v[40:43], v[176:179], v[214:217], v[40:43]
	v_mfma_f32_16x16x32_bf16 v[32:35], v[176:179], v[218:221], v[32:35]
	s_add_u32 m0, s57, 0x8000
	s_add_u32 s46, s44, s30
	s_addc_u32 s47, s45, s31
	global_load_lds_dwordx4 v145, s[46:47]
	v_mfma_f32_16x16x32_bf16 v[28:31], v[182:185], v[206:209], v[28:31]
	v_mfma_f32_16x16x32_bf16 v[16:19], v[182:185], v[210:213], v[16:19]
	s_add_u32 m0, s57, 0xa000
	s_add_u32 s46, s44, s36
	s_addc_u32 s47, s45, s37
	global_load_lds_dwordx4 v145, s[46:47]
	v_mfma_f32_16x16x32_bf16 v[24:27], v[182:185], v[214:217], v[24:27]
	v_mfma_f32_16x16x32_bf16 v[12:15], v[182:185], v[218:221], v[12:15]
	s_add_u32 m0, s57, 0xc000
	s_add_u32 s46, s44, s38
	s_addc_u32 s47, s45, s39
	global_load_lds_dwordx4 v145, s[46:47]
	v_mfma_f32_16x16x32_bf16 v[4:7], v[186:189], v[206:209], v[4:7]
	v_mfma_f32_16x16x32_bf16 v[0:3], v[186:189], v[210:213], v[0:3]
	s_add_u32 m0, s57, 0xe000
	s_add_u32 s46, s44, s40
	s_addc_u32 s47, s45, s41
	global_load_lds_dwordx4 v145, s[46:47]
	v_mfma_f32_16x16x32_bf16 v[20:23], v[186:189], v[214:217], v[20:23]
	v_mfma_f32_16x16x32_bf16 v[8:11], v[186:189], v[218:221], v[8:11]
	ds_read_b128 v[172:175], v223 offset:8192
	ds_read_b128 v[176:179], v223 offset:10240
	ds_read_b128 v[182:185], v223 offset:12288
	ds_read_b128 v[186:189], v223 offset:14336
	s_waitcnt lgkmcnt(4)
	v_mfma_f32_16x16x32_bf16 v[124:127], v[156:159], v[190:193], v[124:127]
	v_mfma_f32_16x16x32_bf16 v[116:119], v[156:159], v[194:197], v[116:119]
	v_mfma_f32_16x16x32_bf16 v[120:123], v[156:159], v[198:201], v[120:123]
	v_mfma_f32_16x16x32_bf16 v[112:115], v[156:159], v[202:205], v[112:115]
	v_mfma_f32_16x16x32_bf16 v[108:111], v[160:163], v[190:193], v[108:111]
	v_mfma_f32_16x16x32_bf16 v[100:103], v[160:163], v[194:197], v[100:103]
	v_mfma_f32_16x16x32_bf16 v[104:107], v[160:163], v[198:201], v[104:107]
	v_mfma_f32_16x16x32_bf16 v[96:99], v[160:163], v[202:205], v[96:99]
	v_mfma_f32_16x16x32_bf16 v[92:95], v[164:167], v[190:193], v[92:95]
	v_mfma_f32_16x16x32_bf16 v[84:87], v[164:167], v[194:197], v[84:87]
	v_mfma_f32_16x16x32_bf16 v[88:91], v[164:167], v[198:201], v[88:91]
	v_mfma_f32_16x16x32_bf16 v[80:83], v[164:167], v[202:205], v[80:83]
	v_mfma_f32_16x16x32_bf16 v[76:79], v[168:171], v[190:193], v[76:79]
	v_mfma_f32_16x16x32_bf16 v[68:71], v[168:171], v[194:197], v[68:71]
	v_mfma_f32_16x16x32_bf16 v[72:75], v[168:171], v[198:201], v[72:75]
	v_mfma_f32_16x16x32_bf16 v[64:67], v[168:171], v[202:205], v[64:67]
	ds_read_b128 v[156:159], v224
	ds_read_b128 v[160:163], v224 offset:2048
	ds_read_b128 v[164:167], v224 offset:4096
	ds_read_b128 v[168:171], v224 offset:6144
	ds_read_b128 v[206:209], v226 offset:32768
	ds_read_b128 v[210:213], v226 offset:34816
	ds_read_b128 v[214:217], v226 offset:36864
	ds_read_b128 v[218:221], v226 offset:38912
	s_waitcnt lgkmcnt(8)
	v_mfma_f32_16x16x32_bf16 v[60:63], v[172:175], v[190:193], v[60:63]
	v_mfma_f32_16x16x32_bf16 v[52:55], v[172:175], v[194:197], v[52:55]
	v_mfma_f32_16x16x32_bf16 v[56:59], v[172:175], v[198:201], v[56:59]
	v_mfma_f32_16x16x32_bf16 v[48:51], v[172:175], v[202:205], v[48:51]
	v_mfma_f32_16x16x32_bf16 v[44:47], v[176:179], v[190:193], v[44:47]
	v_mfma_f32_16x16x32_bf16 v[36:39], v[176:179], v[194:197], v[36:39]
	v_mfma_f32_16x16x32_bf16 v[40:43], v[176:179], v[198:201], v[40:43]
	v_mfma_f32_16x16x32_bf16 v[32:35], v[176:179], v[202:205], v[32:35]
	v_mfma_f32_16x16x32_bf16 v[28:31], v[182:185], v[190:193], v[28:31]
	v_mfma_f32_16x16x32_bf16 v[16:19], v[182:185], v[194:197], v[16:19]
	v_mfma_f32_16x16x32_bf16 v[24:27], v[182:185], v[198:201], v[24:27]
	v_mfma_f32_16x16x32_bf16 v[12:15], v[182:185], v[202:205], v[12:15]
	v_mfma_f32_16x16x32_bf16 v[4:7], v[186:189], v[190:193], v[4:7]
	v_mfma_f32_16x16x32_bf16 v[0:3], v[186:189], v[194:197], v[0:3]
	v_mfma_f32_16x16x32_bf16 v[20:23], v[186:189], v[198:201], v[20:23]
	v_mfma_f32_16x16x32_bf16 v[8:11], v[186:189], v[202:205], v[8:11]
	ds_read_b128 v[172:175], v224 offset:8192
	ds_read_b128 v[176:179], v224 offset:10240
	ds_read_b128 v[182:185], v224 offset:12288
	ds_read_b128 v[186:189], v224 offset:14336
	s_waitcnt lgkmcnt(4)
	v_mfma_f32_16x16x32_bf16 v[124:127], v[156:159], v[206:209], v[124:127]
	v_mfma_f32_16x16x32_bf16 v[116:119], v[156:159], v[210:213], v[116:119]
	v_mfma_f32_16x16x32_bf16 v[120:123], v[156:159], v[214:217], v[120:123]
	v_mfma_f32_16x16x32_bf16 v[112:115], v[156:159], v[218:221], v[112:115]
	v_mfma_f32_16x16x32_bf16 v[108:111], v[160:163], v[206:209], v[108:111]
	v_mfma_f32_16x16x32_bf16 v[100:103], v[160:163], v[210:213], v[100:103]
	v_mfma_f32_16x16x32_bf16 v[104:107], v[160:163], v[214:217], v[104:107]
	v_mfma_f32_16x16x32_bf16 v[96:99], v[160:163], v[218:221], v[96:99]
	v_mfma_f32_16x16x32_bf16 v[92:95], v[164:167], v[206:209], v[92:95]
	v_mfma_f32_16x16x32_bf16 v[84:87], v[164:167], v[210:213], v[84:87]
	v_mfma_f32_16x16x32_bf16 v[88:91], v[164:167], v[214:217], v[88:91]
	v_mfma_f32_16x16x32_bf16 v[80:83], v[164:167], v[218:221], v[80:83]
	v_mfma_f32_16x16x32_bf16 v[76:79], v[168:171], v[206:209], v[76:79]
	v_mfma_f32_16x16x32_bf16 v[68:71], v[168:171], v[210:213], v[68:71]
	v_mfma_f32_16x16x32_bf16 v[72:75], v[168:171], v[214:217], v[72:75]
	v_mfma_f32_16x16x32_bf16 v[64:67], v[168:171], v[218:221], v[64:67]
	s_add_u32 s44, s44, 0x80
	s_addc_u32 s45, s45, 0
	s_add_i32 s43, s43, 1
	s_branch .Lg10_top

.Lg11_top:
	s_waitcnt lgkmcnt(0)
	s_waitcnt vmcnt(0)
	s_barrier
	s_xor_b32 s45, s45, 0x10000
	s_mov_b32 m0, s45
	s_add_u32 s38, s36, s12
	s_addc_u32 s39, s37, s13
	global_load_lds_dwordx4 v178, s[38:39]
	ds_read_b128 v[142:145], v141
	ds_read_b128 v[146:149], v141 offset:2048
	ds_read_b128 v[150:153], v141 offset:4096
	ds_read_b128 v[154:157], v141 offset:6144
	ds_read_b128 v[174:177], v210 offset:32768
	ds_read_b128 v[182:185], v210 offset:34816
	ds_read_b128 v[186:189], v210 offset:36864
	ds_read_b128 v[190:193], v210 offset:38912
	v_mfma_f32_16x16x32_bf16 v[60:63], v[158:161], v[194:197], v[60:63]
	v_mfma_f32_16x16x32_bf16 v[56:59], v[158:161], v[198:201], v[56:59]
	s_add_u32 m0, s45, 0x2000
	s_add_u32 s38, s36, s14
	s_addc_u32 s39, s37, s15
	global_load_lds_dwordx4 v178, s[38:39]
	v_mfma_f32_16x16x32_bf16 v[52:55], v[158:161], v[202:205], v[52:55]
	v_mfma_f32_16x16x32_bf16 v[48:51], v[158:161], v[206:209], v[48:51]
	s_add_u32 m0, s45, 0x4000
	s_add_u32 s38, s36, s16
	s_addc_u32 s39, s37, s17
	global_load_lds_dwordx4 v178, s[38:39]
	v_mfma_f32_16x16x32_bf16 v[44:47], v[162:165], v[194:197], v[44:47]
	v_mfma_f32_16x16x32_bf16 v[32:35], v[162:165], v[198:201], v[32:35]
	s_add_u32 m0, s45, 0x6000
	s_add_u32 s38, s36, s18
	s_addc_u32 s39, s37, s19
	global_load_lds_dwordx4 v178, s[38:39]
	v_mfma_f32_16x16x32_bf16 v[28:31], v[162:165], v[202:205], v[28:31]
	v_mfma_f32_16x16x32_bf16 v[24:27], v[162:165], v[206:209], v[24:27]
	s_add_u32 m0, s45, 0x8000
	s_add_u32 s38, s36, s22
	s_addc_u32 s39, s37, s23
	global_load_lds_dwordx4 v179, s[38:39]
	v_mfma_f32_16x16x32_bf16 v[20:23], v[166:169], v[194:197], v[20:23]
	v_mfma_f32_16x16x32_bf16 v[16:19], v[166:169], v[198:201], v[16:19]
	s_add_u32 m0, s45, 0xa000
	s_add_u32 s38, s36, s24
	s_addc_u32 s39, s37, s25
	global_load_lds_dwordx4 v179, s[38:39]
	v_mfma_f32_16x16x32_bf16 v[12:15], v[166:169], v[202:205], v[12:15]
	v_mfma_f32_16x16x32_bf16 v[8:11], v[166:169], v[206:209], v[8:11]
	s_add_u32 m0, s45, 0xc000
	s_add_u32 s38, s36, s26
	s_addc_u32 s39, s37, s27
	global_load_lds_dwordx4 v179, s[38:39]
	v_mfma_f32_16x16x32_bf16 v[4:7], v[170:173], v[194:197], v[4:7]
	v_mfma_f32_16x16x32_bf16 v[0:3], v[170:173], v[198:201], v[0:3]
	s_add_u32 m0, s45, 0xe000
	s_add_u32 s38, s36, s28
	s_addc_u32 s39, s37, s29
	global_load_lds_dwordx4 v179, s[38:39]
	v_mfma_f32_16x16x32_bf16 v[40:43], v[170:173], v[202:205], v[40:43]
	v_mfma_f32_16x16x32_bf16 v[36:39], v[170:173], v[206:209], v[36:39]
.Lg11_entry:
	ds_read_b128 v[158:161], v141 offset:8192
	ds_read_b128 v[162:165], v141 offset:10240
	ds_read_b128 v[166:169], v141 offset:12288
	ds_read_b128 v[170:173], v141 offset:14336
	s_waitcnt lgkmcnt(4)
	v_mfma_f32_16x16x32_bf16 v[124:127], v[142:145], v[174:177], v[124:127]
	v_mfma_f32_16x16x32_bf16 v[120:123], v[142:145], v[182:185], v[120:123]
	v_mfma_f32_16x16x32_bf16 v[116:119], v[142:145], v[186:189], v[116:119]
	v_mfma_f32_16x16x32_bf16 v[112:115], v[142:145], v[190:193], v[112:115]
	v_mfma_f32_16x16x32_bf16 v[108:111], v[146:149], v[174:177], v[108:111]
	v_mfma_f32_16x16x32_bf16 v[104:107], v[146:149], v[182:185], v[104:107]
	v_mfma_f32_16x16x32_bf16 v[100:103], v[146:149], v[186:189], v[100:103]
	v_mfma_f32_16x16x32_bf16 v[96:99], v[146:149], v[190:193], v[96:99]
	v_mfma_f32_16x16x32_bf16 v[92:95], v[150:153], v[174:177], v[92:95]
	v_mfma_f32_16x16x32_bf16 v[88:91], v[150:153], v[182:185], v[88:91]
	v_mfma_f32_16x16x32_bf16 v[84:87], v[150:153], v[186:189], v[84:87]
	v_mfma_f32_16x16x32_bf16 v[80:83], v[150:153], v[190:193], v[80:83]
	v_mfma_f32_16x16x32_bf16 v[76:79], v[154:157], v[174:177], v[76:79]
	v_mfma_f32_16x16x32_bf16 v[72:75], v[154:157], v[182:185], v[72:75]
	v_mfma_f32_16x16x32_bf16 v[68:71], v[154:157], v[186:189], v[68:71]
	v_mfma_f32_16x16x32_bf16 v[64:67], v[154:157], v[190:193], v[64:67]
	ds_read_b128 v[142:145], v180
	ds_read_b128 v[146:149], v180 offset:2048
	ds_read_b128 v[150:153], v180 offset:4096
	ds_read_b128 v[154:157], v180 offset:6144
	ds_read_b128 v[194:197], v211 offset:32768
	ds_read_b128 v[198:201], v211 offset:34816
	ds_read_b128 v[202:205], v211 offset:36864
	ds_read_b128 v[206:209], v211 offset:38912
	s_waitcnt lgkmcnt(8)
	v_mfma_f32_16x16x32_bf16 v[60:63], v[158:161], v[174:177], v[60:63]
	v_mfma_f32_16x16x32_bf16 v[56:59], v[158:161], v[182:185], v[56:59]
	v_mfma_f32_16x16x32_bf16 v[52:55], v[158:161], v[186:189], v[52:55]
	v_mfma_f32_16x16x32_bf16 v[48:51], v[158:161], v[190:193], v[48:51]
	v_mfma_f32_16x16x32_bf16 v[44:47], v[162:165], v[174:177], v[44:47]
	v_mfma_f32_16x16x32_bf16 v[32:35], v[162:165], v[182:185], v[32:35]
	v_mfma_f32_16x16x32_bf16 v[28:31], v[162:165], v[186:189], v[28:31]
	v_mfma_f32_16x16x32_bf16 v[24:27], v[162:165], v[190:193], v[24:27]
	v_mfma_f32_16x16x32_bf16 v[20:23], v[166:169], v[174:177], v[20:23]
	v_mfma_f32_16x16x32_bf16 v[16:19], v[166:169], v[182:185], v[16:19]
	v_mfma_f32_16x16x32_bf16 v[12:15], v[166:169], v[186:189], v[12:15]
	v_mfma_f32_16x16x32_bf16 v[8:11], v[166:169], v[190:193], v[8:11]
	v_mfma_f32_16x16x32_bf16 v[4:7], v[170:173], v[174:177], v[4:7]
	v_mfma_f32_16x16x32_bf16 v[0:3], v[170:173], v[182:185], v[0:3]
	v_mfma_f32_16x16x32_bf16 v[40:43], v[170:173], v[186:189], v[40:43]
	v_mfma_f32_16x16x32_bf16 v[36:39], v[170:173], v[190:193], v[36:39]
	ds_read_b128 v[158:161], v180 offset:8192
	ds_read_b128 v[162:165], v180 offset:10240
	ds_read_b128 v[166:169], v180 offset:12288
	ds_read_b128 v[170:173], v180 offset:14336
	s_waitcnt lgkmcnt(4)
	v_mfma_f32_16x16x32_bf16 v[124:127], v[142:145], v[194:197], v[124:127]
	v_mfma_f32_16x16x32_bf16 v[120:123], v[142:145], v[198:201], v[120:123]
	v_mfma_f32_16x16x32_bf16 v[116:119], v[142:145], v[202:205], v[116:119]
	v_mfma_f32_16x16x32_bf16 v[112:115], v[142:145], v[206:209], v[112:115]
	v_mfma_f32_16x16x32_bf16 v[108:111], v[146:149], v[194:197], v[108:111]
	v_mfma_f32_16x16x32_bf16 v[104:107], v[146:149], v[198:201], v[104:107]
	v_mfma_f32_16x16x32_bf16 v[100:103], v[146:149], v[202:205], v[100:103]
	v_mfma_f32_16x16x32_bf16 v[96:99], v[146:149], v[206:209], v[96:99]
	v_mfma_f32_16x16x32_bf16 v[92:95], v[150:153], v[194:197], v[92:95]
	v_mfma_f32_16x16x32_bf16 v[88:91], v[150:153], v[198:201], v[88:91]
	v_mfma_f32_16x16x32_bf16 v[84:87], v[150:153], v[202:205], v[84:87]
	v_mfma_f32_16x16x32_bf16 v[80:83], v[150:153], v[206:209], v[80:83]
	v_mfma_f32_16x16x32_bf16 v[76:79], v[154:157], v[194:197], v[76:79]
	v_mfma_f32_16x16x32_bf16 v[72:75], v[154:157], v[198:201], v[72:75]
	v_mfma_f32_16x16x32_bf16 v[68:71], v[154:157], v[202:205], v[68:71]
	v_mfma_f32_16x16x32_bf16 v[64:67], v[154:157], v[206:209], v[64:67]
	s_add_u32 s36, s36, 0x80
	s_addc_u32 s37, s37, 0
	s_add_i32 s31, s31, 1
	s_cmp_lt_u32 s31, 31
	s_cbranch_scc0 .Lg11_last
	s_waitcnt lgkmcnt(0)
	s_waitcnt vmcnt(0)
	s_barrier
	s_xor_b32 s45, s45, 0x10000
	s_mov_b32 m0, s45
	s_add_u32 s38, s36, s12
	s_addc_u32 s39, s37, s13
	global_load_lds_dwordx4 v178, s[38:39]
	ds_read_b128 v[142:145], v212
	ds_read_b128 v[146:149], v212 offset:2048
	ds_read_b128 v[150:153], v212 offset:4096
	ds_read_b128 v[154:157], v212 offset:6144
	ds_read_b128 v[174:177], v214 offset:32768
	ds_read_b128 v[182:185], v214 offset:34816
	ds_read_b128 v[186:189], v214 offset:36864
	ds_read_b128 v[190:193], v214 offset:38912
	v_mfma_f32_16x16x32_bf16 v[60:63], v[158:161], v[194:197], v[60:63]
	v_mfma_f32_16x16x32_bf16 v[56:59], v[158:161], v[198:201], v[56:59]
	s_add_u32 m0, s45, 0x2000
	s_add_u32 s38, s36, s14
	s_addc_u32 s39, s37, s15
	global_load_lds_dwordx4 v178, s[38:39]
	v_mfma_f32_16x16x32_bf16 v[52:55], v[158:161], v[202:205], v[52:55]
	v_mfma_f32_16x16x32_bf16 v[48:51], v[158:161], v[206:209], v[48:51]
	s_add_u32 m0, s45, 0x4000
	s_add_u32 s38, s36, s16
	s_addc_u32 s39, s37, s17
	global_load_lds_dwordx4 v178, s[38:39]
	v_mfma_f32_16x16x32_bf16 v[44:47], v[162:165], v[194:197], v[44:47]
	v_mfma_f32_16x16x32_bf16 v[32:35], v[162:165], v[198:201], v[32:35]
	s_add_u32 m0, s45, 0x6000
	s_add_u32 s38, s36, s18
	s_addc_u32 s39, s37, s19
	global_load_lds_dwordx4 v178, s[38:39]
	v_mfma_f32_16x16x32_bf16 v[28:31], v[162:165], v[202:205], v[28:31]
	v_mfma_f32_16x16x32_bf16 v[24:27], v[162:165], v[206:209], v[24:27]
	s_add_u32 m0, s45, 0x8000
	s_add_u32 s38, s36, s22
	s_addc_u32 s39, s37, s23
	global_load_lds_dwordx4 v179, s[38:39]
	v_mfma_f32_16x16x32_bf16 v[20:23], v[166:169], v[194:197], v[20:23]
	v_mfma_f32_16x16x32_bf16 v[16:19], v[166:169], v[198:201], v[16:19]
	s_add_u32 m0, s45, 0xa000
	s_add_u32 s38, s36, s24
	s_addc_u32 s39, s37, s25
	global_load_lds_dwordx4 v179, s[38:39]
	v_mfma_f32_16x16x32_bf16 v[12:15], v[166:169], v[202:205], v[12:15]
	v_mfma_f32_16x16x32_bf16 v[8:11], v[166:169], v[206:209], v[8:11]
	s_add_u32 m0, s45, 0xc000
	s_add_u32 s38, s36, s26
	s_addc_u32 s39, s37, s27
	global_load_lds_dwordx4 v179, s[38:39]
	v_mfma_f32_16x16x32_bf16 v[4:7], v[170:173], v[194:197], v[4:7]
	v_mfma_f32_16x16x32_bf16 v[0:3], v[170:173], v[198:201], v[0:3]
	s_add_u32 m0, s45, 0xe000
	s_add_u32 s38, s36, s28
	s_addc_u32 s39, s37, s29
	global_load_lds_dwordx4 v179, s[38:39]
	v_mfma_f32_16x16x32_bf16 v[40:43], v[170:173], v[202:205], v[40:43]
	v_mfma_f32_16x16x32_bf16 v[36:39], v[170:173], v[206:209], v[36:39]
	ds_read_b128 v[158:161], v212 offset:8192
	ds_read_b128 v[162:165], v212 offset:10240
	ds_read_b128 v[166:169], v212 offset:12288
	ds_read_b128 v[170:173], v212 offset:14336
	s_waitcnt lgkmcnt(4)
	v_mfma_f32_16x16x32_bf16 v[124:127], v[142:145], v[174:177], v[124:127]
	v_mfma_f32_16x16x32_bf16 v[120:123], v[142:145], v[182:185], v[120:123]
	v_mfma_f32_16x16x32_bf16 v[116:119], v[142:145], v[186:189], v[116:119]
	v_mfma_f32_16x16x32_bf16 v[112:115], v[142:145], v[190:193], v[112:115]
	v_mfma_f32_16x16x32_bf16 v[108:111], v[146:149], v[174:177], v[108:111]
	v_mfma_f32_16x16x32_bf16 v[104:107], v[146:149], v[182:185], v[104:107]
	v_mfma_f32_16x16x32_bf16 v[100:103], v[146:149], v[186:189], v[100:103]
	v_mfma_f32_16x16x32_bf16 v[96:99], v[146:149], v[190:193], v[96:99]
	v_mfma_f32_16x16x32_bf16 v[92:95], v[150:153], v[174:177], v[92:95]
	v_mfma_f32_16x16x32_bf16 v[88:91], v[150:153], v[182:185], v[88:91]
	v_mfma_f32_16x16x32_bf16 v[84:87], v[150:153], v[186:189], v[84:87]
	v_mfma_f32_16x16x32_bf16 v[80:83], v[150:153], v[190:193], v[80:83]
	v_mfma_f32_16x16x32_bf16 v[76:79], v[154:157], v[174:177], v[76:79]
	v_mfma_f32_16x16x32_bf16 v[72:75], v[154:157], v[182:185], v[72:75]
	v_mfma_f32_16x16x32_bf16 v[68:71], v[154:157], v[186:189], v[68:71]
	v_mfma_f32_16x16x32_bf16 v[64:67], v[154:157], v[190:193], v[64:67]
	ds_read_b128 v[142:145], v213
	ds_read_b128 v[146:149], v213 offset:2048
	ds_read_b128 v[150:153], v213 offset:4096
	ds_read_b128 v[154:157], v213 offset:6144
	ds_read_b128 v[194:197], v215 offset:32768
	ds_read_b128 v[198:201], v215 offset:34816
	ds_read_b128 v[202:205], v215 offset:36864
	ds_read_b128 v[206:209], v215 offset:38912
	s_waitcnt lgkmcnt(8)
	v_mfma_f32_16x16x32_bf16 v[60:63], v[158:161], v[174:177], v[60:63]
	v_mfma_f32_16x16x32_bf16 v[56:59], v[158:161], v[182:185], v[56:59]
	v_mfma_f32_16x16x32_bf16 v[52:55], v[158:161], v[186:189], v[52:55]
	v_mfma_f32_16x16x32_bf16 v[48:51], v[158:161], v[190:193], v[48:51]
	v_mfma_f32_16x16x32_bf16 v[44:47], v[162:165], v[174:177], v[44:47]
	v_mfma_f32_16x16x32_bf16 v[32:35], v[162:165], v[182:185], v[32:35]
	v_mfma_f32_16x16x32_bf16 v[28:31], v[162:165], v[186:189], v[28:31]
	v_mfma_f32_16x16x32_bf16 v[24:27], v[162:165], v[190:193], v[24:27]
	v_mfma_f32_16x16x32_bf16 v[20:23], v[166:169], v[174:177], v[20:23]
	v_mfma_f32_16x16x32_bf16 v[16:19], v[166:169], v[182:185], v[16:19]
	v_mfma_f32_16x16x32_bf16 v[12:15], v[166:169], v[186:189], v[12:15]
	v_mfma_f32_16x16x32_bf16 v[8:11], v[166:169], v[190:193], v[8:11]
	v_mfma_f32_16x16x32_bf16 v[4:7], v[170:173], v[174:177], v[4:7]
	v_mfma_f32_16x16x32_bf16 v[0:3], v[170:173], v[182:185], v[0:3]
	v_mfma_f32_16x16x32_bf16 v[40:43], v[170:173], v[186:189], v[40:43]
	v_mfma_f32_16x16x32_bf16 v[36:39], v[170:173], v[190:193], v[36:39]
	ds_read_b128 v[158:161], v213 offset:8192
	ds_read_b128 v[162:165], v213 offset:10240
	ds_read_b128 v[166:169], v213 offset:12288
	ds_read_b128 v[170:173], v213 offset:14336
	s_waitcnt lgkmcnt(4)
	v_mfma_f32_16x16x32_bf16 v[124:127], v[142:145], v[194:197], v[124:127]
	v_mfma_f32_16x16x32_bf16 v[120:123], v[142:145], v[198:201], v[120:123]
	v_mfma_f32_16x16x32_bf16 v[116:119], v[142:145], v[202:205], v[116:119]
	v_mfma_f32_16x16x32_bf16 v[112:115], v[142:145], v[206:209], v[112:115]
	v_mfma_f32_16x16x32_bf16 v[108:111], v[146:149], v[194:197], v[108:111]
	v_mfma_f32_16x16x32_bf16 v[104:107], v[146:149], v[198:201], v[104:107]
	v_mfma_f32_16x16x32_bf16 v[100:103], v[146:149], v[202:205], v[100:103]
	v_mfma_f32_16x16x32_bf16 v[96:99], v[146:149], v[206:209], v[96:99]
	v_mfma_f32_16x16x32_bf16 v[92:95], v[150:153], v[194:197], v[92:95]
	v_mfma_f32_16x16x32_bf16 v[88:91], v[150:153], v[198:201], v[88:91]
	v_mfma_f32_16x16x32_bf16 v[84:87], v[150:153], v[202:205], v[84:87]
	v_mfma_f32_16x16x32_bf16 v[80:83], v[150:153], v[206:209], v[80:83]
	v_mfma_f32_16x16x32_bf16 v[76:79], v[154:157], v[194:197], v[76:79]
	v_mfma_f32_16x16x32_bf16 v[72:75], v[154:157], v[198:201], v[72:75]
	v_mfma_f32_16x16x32_bf16 v[68:71], v[154:157], v[202:205], v[68:71]
	v_mfma_f32_16x16x32_bf16 v[64:67], v[154:157], v[206:209], v[64:67]
	s_add_u32 s36, s36, 0x80
	s_addc_u32 s37, s37, 0
	s_add_i32 s31, s31, 1
	s_branch .Lg11_top
